# REC: gate-scalar loads of GDN/SSD chunk loops no longer waited right after issue; SSD chunked scan LDS reads issued in bursts into spare registers with counted lgkmcnt
# speedup vs baseline: 1.0244x; 1.0233x over previous
; #define LAS __attribute__((address_space(3)))
; __device__ __forceinline__ float hload(const f16_t* p) { return (float)(*p); }
; __device__ __forceinline__ int tidx() { int t = threadIdx.x; asm volatile("" : "+v"(t)); return t; }
; __device__ __forceinline__ unsigned char* pws() { return kargs()->ws; }
; template <int MIX, bool SAMPLE>
; __device__ __forceinline__ void rec_load(Raw<MIX>& R, const f16_t* proj, int chunk, int sg, int head, int vcol0) {
;     ...
;     } else {
;         const f16_t* pb = rowp + C_SXBC + 256 + (head >> 1) * 128 + cgi * 16;
;         R.b[0] = *(const u32x4*)pb; R.b[1] = *(const u32x4*)(pb + 8); R.c[0] = *(const u32x4*)(pb + 256); R.c[1] = *(const u32x4*)(pb + 264);
;         R.x = *(const u32x2*)(rowp + C_SXBC + head * 64 + vcol0 + cgi * 4);
;         R.dt = hload(rowp + C_SDT + head);
;     }
; template <int MIX>
; __device__ __forceinline__ void rec_unit_chunked(const Params& p, int l, LAS unsigned char* lds, int sg, int head, int vhalf) {
;     typedef ChCfg<MIX> C; constexpr int K = C::K;
;     const f16_t* proj = (const f16_t*)(pws() + WS_PROJ);
;     f16_t* raw = (f16_t*)(pws() + WS_XN);
;     const int tid = tidx(), w = __builtin_amdgcn_readfirstlane(tid >> 6), lane = tid & 63;
;     constexpr long o_p = MIX == 2 ? O_RET_P : O_SSD_P;
;     Raw<MIX> R;
;     const MixPar par = mix_par<MIX>(l, head);
;     f32x4 St[K / 16];
; #pragma unroll
;     for (int i = 0; i < K / 16; ++i) St[i] = (f32x4){0.f, 0.f, 0.f, 0.f};
;     rec_load<MIX, false>(R, proj, 0, sg, head, vhalf * 32);
; #pragma unroll 1
;     for (int c = 0; c < SEQ / 64; ++c) {
;         ch_process<MIX>(R, par, lds, c);
;         __syncthreads();
;         if (c + 1 < SEQ / 64) rec_load<MIX, false>(R, proj, c + 1, sg, head, vhalf * 32);
.LBB0_175:
	s_ashr_i32 s31, s40, 5
	s_lshl_b32 s2, s31, 3
	s_and_b32 s3, s40, 7
	s_and_b32 s35, s41, 7
	s_and_b32 s34, s40, 1
	s_bfe_u32 s30, s40, 0x20001
	s_bfe_u32 s25, s40, 0x20003
	s_or_b32 s77, s2, s3
	s_mul_i32 s59, s35, 0x84
	s_cmp_lt_i32 s25, 2
	s_mov_b64 s[4:5], -1
	s_cbranch_scc1 .LBB0_334
	s_lshr_b32 s2, s40, 1
	s_and_b32 s2, s2, 3
	s_waitcnt vmcnt(2)
	v_cndmask_b32_e64 v0, 0, 1, s[84:85]
	s_lshl_b32 s94, s2, 14
	s_waitcnt vmcnt(0)
	v_lshlrev_b32_e32 v67, 5, v0
	s_mov_b32 s95, s79
	s_cmp_gt_i32 s25, 2
	v_writelane_b32 v252, s2, 62
	s_cbranch_scc0 .LBB0_257
	s_mov_b64 s[2:3], s[0:1]
	s_mov_b64 s[4:5], s[0:1]
	s_load_dwordx2 s[2:3], s[2:3], 0xe0
	s_load_dwordx2 s[52:53], s[4:5], 0xe0
	v_mov_b32_e32 v64, v202
	v_mov_b32_e32 v0, v202
	s_mov_b64 s[4:5], s[0:1]
	s_load_dwordx2 s[4:5], s[4:5], 0x90
	v_readlane_b32 s6, v252, 59
	s_or_b32 s6, s30, s6
	s_lshl_b32 s7, s6, 2
	v_mov_b32_e32 v0, s7
	s_waitcnt lgkmcnt(0)
	global_load_dword v65, v0, s[4:5]
	s_mov_b64 s[4:5], s[0:1]
	s_load_dwordx2 s[4:5], s[4:5], 0x98
	v_readfirstlane_b32 s10, v64
	s_ashr_i32 s9, s10, 6
	s_add_u32 s54, s2, 0x5600000
	v_mov_b32_e32 v6, v202
	s_waitcnt lgkmcnt(0)
	global_load_dword v23, v0, s[4:5]
	s_mov_b64 s[4:5], s[0:1]
	s_load_dwordx2 s[4:5], s[4:5], 0xa0
	s_addc_u32 s55, s3, 0
	s_lshl_b32 s7, s31, 11
	s_lshl_b32 s83, s30, 6
	s_mov_b64 s[60:61], 0x1c10
	s_waitcnt lgkmcnt(0)
	global_load_dword v58, v0, s[4:5]
	s_lshl_b32 s82, s34, 5
	v_ashrrev_i32_e32 v0, 3, v6
	v_add_u32_e32 v2, s7, v0
	v_mov_b64_e32 v[0:1], s[54:55]
	v_mad_i64_i32 v[0:1], s[2:3], v2, s18, v[0:1]
	s_and_b32 s2, s83, 0x80
	s_lshl_b32 s78, s2, 1
	v_lshl_add_u64 v[2:3], v[0:1], 0, s[78:79]
	s_lshl_b32 s78, s30, 7
	v_lshl_add_u64 v[4:5], v[0:1], 0, s[78:79]
	s_lshl_b32 s78, s34, 6
	v_lshl_add_u64 v[4:5], v[4:5], 0, s[78:79]
	s_lshl_b32 s78, s30, 1
	v_lshl_add_u64 v[0:1], v[0:1], 0, s[78:79]
	s_movk_i32 s3, 0x2000
	v_add_co_u32_e32 v0, vcc, s3, v0
	v_and_b32_e32 v6, 7, v6
	s_nop 0
	v_addc_co_u32_e32 v1, vcc, 0, v1, vcc
	global_load_ushort v24, v[0:1], off offset:16
	v_lshlrev_b32_e32 v16, 5, v6
	v_lshl_add_u64 v[0:1], v[2:3], 0, v[16:17]
	v_lshlrev_b32_e32 v16, 3, v6
	v_lshl_add_u64 v[12:13], v[0:1], 0, s[60:61]
	v_add_co_u32_e32 v0, vcc, s20, v0
	v_lshl_add_u64 v[14:15], v[4:5], 0, v[16:17]
	s_nop 0
	v_addc_co_u32_e32 v1, vcc, 0, v1, vcc
	global_load_dwordx4 v[0:3], v[0:1], off offset:3088
	s_nop 0
	global_load_dwordx4 v[4:7], v[12:13], off offset:528
	global_load_dwordx4 v[8:11], v[12:13], off offset:16
	global_load_dwordx4 v[18:21], v[12:13], off offset:512
	v_add_co_u32_e32 v12, vcc, s20, v14
	v_bfe_u32 v27, v64, 2, 4
	s_nop 0
	v_addc_co_u32_e32 v13, vcc, 0, v15, vcc
	global_load_dwordx2 v[60:61], v[12:13], off offset:2576
	s_cmp_lt_i32 s9, 2
	v_and_b32_e32 v66, 15, v64
	v_and_b32_e32 v28, 12, v27
	s_cselect_b64 s[56:57], -1, 0
	s_lshl_b32 s9, s9, 4
	s_andn2_b32 s10, s10, 63
	v_and_b32_e32 v25, 63, v64
	v_or_b32_e32 v12, s9, v66
	s_add_i32 s3, s10, 0
	v_lshlrev_b32_e32 v29, 2, v66
	s_movk_i32 s11, 0x110
	v_readlane_b32 s4, v253, 58
	v_mul_lo_u32 v12, v12, s28
	s_add_i32 s3, s3, 0x14c00
	v_add_u32_e32 v70, s4, v29
	v_add_u32_e32 v72, s24, v12
	v_add_u32_e32 v12, s3, v29
	v_lshlrev_b32_e32 v69, 1, v28
	v_lshlrev_b32_e32 v32, 2, v28
	v_readlane_b32 s3, v253, 59
	v_add_u32_e32 v71, 0, v69
	v_mov_b32_e32 v22, 0
	v_add_u32_e32 v80, s3, v32
	v_readlane_b32 s3, v253, 60
	v_and_b32_e32 v26, 48, v64
	v_mul_u32_u24_e32 v68, 0x90, v66
	v_mul_u32_u24_e32 v30, 0x110, v66
	v_mad_u32_u24 v31, v66, s11, 0
	v_cmp_gt_u32_e64 s[42:43], v28, v66
	v_cmp_lt_u32_e64 s[44:45], v28, v66
	v_add_u32_e32 v16, 0xcc00, v71
	v_add_u32_e32 v84, s3, v32
	s_waitcnt vmcnt(7)
	v_mul_f32_e32 v13, 0x3fb8aa3b, v23
	v_fma_f32 v14, v23, s19, -v13
	v_rndne_f32_e32 v15, v13
	v_fmac_f32_e32 v14, 0x32a5705f, v23
	v_sub_f32_e32 v13, v13, v15
	v_add_f32_e32 v13, v13, v14
	v_cvt_i32_f32_e32 v15, v15
	v_exp_f32_e32 v13, v13
	v_cmp_ngt_f32_e32 vcc, s96, v23
	v_lshlrev_b32_e32 v14, 7, v27
	v_or_b32_e32 v33, 0x980, v14
	v_ldexp_f32 v13, v13, v15
	v_cndmask_b32_e32 v13, 0, v13, vcc
	v_cmp_nlt_f32_e32 vcc, s97, v23
	v_or_b32_e32 v23, 16, v66
	v_mul_u32_u24_e32 v76, 0x90, v23
	v_cndmask_b32_e32 v73, v216, v13, vcc
	v_or_b32_e32 v13, 2, v28
	v_cmp_gt_u32_e64 s[46:47], v13, v66
	v_or_b32_e32 v13, 3, v27
	v_or_b32_e32 v27, 48, v25
	v_or_b32_e32 v25, 0x70, v25
	v_mul_u32_u24_e32 v77, 0x90, v27
	v_mul_u32_u24_e32 v78, 0x90, v25
	v_mul_u32_u24_e32 v25, 0x110, v23
	v_mad_u32_u24 v29, v23, s11, 0
	v_lshl_add_u32 v79, v23, 2, s4
	v_or_b32_e32 v23, 16, v28
	v_mul_u32_u24_e32 v39, 0x110, v27
	v_mad_u32_u24 v40, v27, s11, 0
	v_lshl_add_u32 v87, v27, 2, s4
	s_waitcnt vmcnt(5)
	v_mov_b32_e32 v75, v24
	v_or_b32_e32 v24, 32, v66
	v_mul_u32_u24_e32 v35, 0x110, v24
	v_mad_u32_u24 v36, v24, s11, 0
	v_lshl_add_u32 v83, v24, 2, s4
	v_or_b32_e32 v24, 32, v28
	v_or_b32_e32 v27, 48, v28
	v_lshlrev_b32_e32 v81, 1, v23
	v_lshlrev_b32_e32 v85, 1, v24
	v_lshlrev_b32_e32 v89, 1, v27
	v_add_u32_e32 v82, 0, v81
	v_add_u32_e32 v86, 0, v85
	v_add_u32_e32 v90, 0, v89
	v_cmp_gt_u32_e64 s[48:49], v13, v66
	v_lshlrev_b32_e32 v13, 7, v28
	v_or_b32_e32 v15, 0x180, v14
	v_lshlrev_b32_e32 v23, 7, v23
	v_add_u32_e32 v34, 0xcc00, v82
	v_lshlrev_b32_e32 v24, 7, v24
	v_or_b32_e32 v37, 0x1180, v14
	v_add_u32_e32 v38, 0xcc00, v86
	v_readlane_b32 s3, v253, 61
	v_lshlrev_b32_e32 v27, 7, v27
	v_or_b32_e32 v14, 0x1980, v14
	v_add_u32_e32 v28, 0xcc00, v90
	s_mov_b32 s8, 0
	v_add_u32_e32 v74, s4, v32
	v_add_u32_e32 v88, s3, v32
	v_mov_b32_e32 v62, v58
	v_mov_b32_e32 v63, v58
	s_lshl_b32 s58, s2, 1
	v_add_u32_e32 v91, v31, v26
	v_add_u32_e32 v92, v71, v30
	v_add_u32_e32 v93, v12, v13
	v_add_u32_e32 v94, v12, v15
	v_add_u32_e32 v95, v16, v68
	v_add_u32_e32 v96, v29, v26
	v_add_u32_e32 v97, v71, v25
	v_add_u32_e32 v98, v12, v23
	v_add_u32_e32 v99, v12, v33
	v_add_u32_e32 v100, v34, v68
	v_add_u32_e32 v101, v36, v26
	v_add_u32_e32 v102, v71, v35
	v_add_u32_e32 v103, v12, v24
	v_add_u32_e32 v104, v12, v37
	v_add_u32_e32 v105, v38, v68
	v_add_u32_e32 v106, v40, v26
	v_add_u32_e32 v107, v71, v39
	v_add_u32_e32 v108, v12, v27
	v_add_u32_e32 v109, v12, v14
	v_add_u32_e32 v110, v28, v68
	v_mov_b32_e32 v23, v22
	v_mov_b32_e32 v24, v22
	v_mov_b32_e32 v25, v22
	v_mov_b32_e32 v50, v22
	v_mov_b32_e32 v51, v22
	v_mov_b32_e32 v52, v22
	v_mov_b32_e32 v53, v22
	v_mov_b32_e32 v46, v22
	v_mov_b32_e32 v47, v22
	v_mov_b32_e32 v48, v22
	v_mov_b32_e32 v49, v22
	v_mov_b32_e32 v42, v22
	v_mov_b32_e32 v43, v22
	v_mov_b32_e32 v44, v22
	v_mov_b32_e32 v45, v22
	v_mov_b32_e32 v38, v22
	v_mov_b32_e32 v39, v22
	v_mov_b32_e32 v40, v22
	v_mov_b32_e32 v41, v22
	v_mov_b32_e32 v34, v22
	v_mov_b32_e32 v35, v22
	v_mov_b32_e32 v36, v22
	v_mov_b32_e32 v37, v22
	v_mov_b32_e32 v30, v22
	v_mov_b32_e32 v31, v22
	v_mov_b32_e32 v32, v22
	v_mov_b32_e32 v33, v22
	v_mov_b32_e32 v26, v22
	v_mov_b32_e32 v27, v22
	v_mov_b32_e32 v28, v22
	v_mov_b32_e32 v29, v22
	v_readlane_b32 s10, v253, 62
	v_readlane_b32 s12, v253, 63
	v_readlane_b32 s13, v252, 0
	v_readlane_b32 s17, v252, 1
	s_branch .LBB0_179

; __device__ __forceinline__ void u4f(const u32x4& u, float (&f)[8]) { h2f(u.x, f[0], f[1]); h2f(u.y, f[2], f[3]); h2f(u.z, f[4], f[5]); h2f(u.w, f[6], f[7]); }
; __device__ __forceinline__ void u2f(const u32x2& u, float (&f)[4]) { h2f(u.x, f[0], f[1]); h2f(u.y, f[2], f[3]); }
; __device__ __forceinline__ float softplusf_(float x) { return x > 20.f ? x : log1pf(expf(x)); }
; template <int MIX>
; __device__ __forceinline__ void ch_process(const Raw<MIX>& R, const MixPar& par, LAS unsigned char* B, int chunk) {
;     ...
;         float b0[8], b1[8], c0[8], c1[8], x[4]; u4f(R.b[0], b0); u4f(R.b[1], b1); u4f(R.c[0], c0); u4f(R.c[1], c1); u2f(R.x, x);
;         const float dt = softplusf_(R.dt + par.f[0]);
;         const float la = -par.f[1] * dt, dsk = par.f[2];
.LBB0_179:
	s_waitcnt vmcnt(5)
	v_cvt_f32_f16_e32 v75, v75
	s_nop 0
	v_add_f32_e32 v12, v65, v75
	v_mov_b32_e32 v13, v202
	v_cmp_nlt_f32_e32 vcc, s23, v12
	s_and_saveexec_b64 s[4:5], vcc
	s_cbranch_execz .LBB0_181
	v_mul_f32_e32 v14, 0x3fb8aa3b, v12
	v_rndne_f32_e32 v15, v14
	v_sub_f32_e32 v16, v14, v15
	v_fma_f32 v14, v12, s19, -v14
	v_fmac_f32_e32 v14, 0x32a5705f, v12
	v_add_f32_e32 v14, v16, v14
	v_cvt_i32_f32_e32 v15, v15
	v_exp_f32_e32 v14, v14
	v_cmp_ngt_f32_e32 vcc, s96, v12
	v_ldexp_f32 v14, v14, v15
	s_nop 0
	v_cndmask_b32_e32 v14, 0, v14, vcc
	v_cmp_nlt_f32_e32 vcc, s97, v12
	s_nop 1
	v_cndmask_b32_e32 v12, v216, v14, vcc
	v_add_f32_e32 v16, 1.0, v12
	v_add_f32_e32 v14, -1.0, v16
	v_sub_f32_e32 v15, v14, v16
	v_add_f32_e32 v15, 1.0, v15
	v_sub_f32_e32 v14, v12, v14
	v_add_f32_e32 v54, v14, v15
	v_frexp_mant_f32_e32 v55, v16
	v_cvt_f64_f32_e32 v[14:15], v16
	v_frexp_exp_i32_f64_e32 v14, v[14:15]
	v_cmp_gt_f32_e32 vcc, s62, v55
	s_nop 1
	v_subbrev_co_u32_e32 v59, vcc, 0, v14, vcc
	v_sub_u32_e32 v14, 0, v59
	v_ldexp_f32 v15, v16, v14
	v_add_f32_e32 v16, -1.0, v15
	v_add_f32_e32 v55, 1.0, v15
	v_ldexp_f32 v14, v54, v14
	v_add_f32_e32 v54, 1.0, v16
	v_add_f32_e32 v56, -1.0, v55
	v_sub_f32_e32 v54, v15, v54
	v_sub_f32_e32 v15, v15, v56
	v_add_f32_e32 v54, v14, v54
	v_add_f32_e32 v14, v14, v15
	v_add_f32_e32 v111, v55, v14
	v_rcp_f32_e32 v115, v111
	v_sub_f32_e32 v15, v55, v111
	v_add_f32_e32 v114, v14, v15
	v_add_f32_e32 v15, v16, v54
	v_sub_f32_e32 v14, v16, v15
	v_mul_f32_e32 v116, v15, v115
	v_add_f32_e32 v16, v54, v14
	v_mul_f32_e32 v54, v111, v116
	v_fma_f32 v56, v116, v111, -v54
	v_fmac_f32_e32 v56, v116, v114
	v_add_f32_e32 v14, v54, v56
	v_sub_f32_e32 v55, v15, v14
	v_pk_add_f32 v[112:113], v[14:15], v[54:55] neg_lo:[0,1] neg_hi:[0,1]
	v_mov_b32_e32 v57, v14
	v_pk_add_f32 v[14:15], v[112:113], v[56:57] neg_lo:[0,1] neg_hi:[0,1]
	v_cmp_neq_f32_e32 vcc, s21, v12
	v_add_f32_e32 v15, v16, v15
	v_add_f32_e32 v14, v14, v15
	v_add_f32_e32 v15, v55, v14
	v_mul_f32_e32 v16, v115, v15
	v_mul_f32_e32 v54, v111, v16
	v_fma_f32 v56, v16, v111, -v54
	v_fmac_f32_e32 v56, v16, v114
	v_sub_f32_e32 v55, v55, v15
	v_add_f32_e32 v111, v14, v55
	v_add_f32_e32 v14, v54, v56
	v_sub_f32_e32 v55, v15, v14
	v_pk_add_f32 v[112:113], v[14:15], v[54:55] neg_lo:[0,1] neg_hi:[0,1]
	v_mov_b32_e32 v57, v14
	v_pk_add_f32 v[14:15], v[112:113], v[56:57] neg_lo:[0,1] neg_hi:[0,1]
	s_nop 0
	v_add_f32_e32 v15, v111, v15
	v_add_f32_e32 v14, v14, v15
	v_add_f32_e32 v15, v116, v16
	v_add_f32_e32 v14, v55, v14
	v_sub_f32_e32 v54, v15, v116
	v_mul_f32_e32 v14, v115, v14
	v_sub_f32_e32 v16, v16, v54
	v_add_f32_e32 v16, v16, v14
	v_add_f32_e32 v54, v15, v16
	v_mul_f32_e32 v56, v54, v54
	v_fmamk_f32 v14, v56, 0x3e9b6dac, v204
	v_fmaak_f32 v139, v56, v14, 0x3f2aaada
	v_cvt_f32_i32_e32 v14, v59
	v_sub_f32_e32 v15, v54, v15
	v_sub_f32_e32 v15, v16, v15
	v_ldexp_f32 v16, v15, 1
	v_mul_f32_e32 v15, v54, v56
	v_pk_mul_f32 v[56:57], v[14:15], v[138:139]
	v_ldexp_f32 v55, v54, 1
	v_fma_f32 v54, v14, s63, -v56
	v_fmac_f32_e32 v54, 0xb102e308, v14
	v_pk_add_f32 v[14:15], v[56:57], v[54:55]
	v_mov_b32_e32 v112, v56
	v_sub_f32_e32 v55, v15, v55
	v_sub_f32_e32 v55, v57, v55
	v_add_f32_e32 v113, v16, v55
	v_pk_add_f32 v[56:57], v[14:15], v[56:57] neg_lo:[0,1] neg_hi:[0,1]
	v_pk_add_f32 v[114:115], v[14:15], v[112:113]
	v_mov_b32_e32 v55, v14
	v_mov_b32_e32 v57, v115
	v_pk_add_f32 v[116:117], v[54:55], v[56:57] neg_lo:[0,1] neg_hi:[0,1]
	v_pk_add_f32 v[54:55], v[54:55], v[56:57]
	v_mov_b32_e32 v112, v113
	v_pk_add_f32 v[56:57], v[54:55], v[14:15] op_sel:[1,0] op_sel_hi:[0,1] neg_lo:[0,1] neg_hi:[0,1]
	v_pk_add_f32 v[118:119], v[114:115], v[56:57] op_sel_hi:[1,0] neg_lo:[0,1] neg_hi:[0,1]
	v_mov_b32_e32 v114, v115
	v_mov_b32_e32 v115, v55
	v_pk_mov_b32 v[56:57], v[14:15], v[56:57] op_sel:[1,0]
	v_mov_b32_e32 v113, v14
	v_pk_add_f32 v[56:57], v[114:115], v[56:57] neg_lo:[0,1] neg_hi:[0,1]
	v_mov_b32_e32 v118, v116
	v_pk_add_f32 v[14:15], v[112:113], v[56:57] neg_lo:[0,1] neg_hi:[0,1]
	v_mov_b32_e32 v117, v55
	v_pk_add_f32 v[56:57], v[118:119], v[14:15]
	s_nop 0
	v_pk_add_f32 v[112:113], v[56:57], v[56:57] op_sel:[0,1] op_sel_hi:[1,0]
	s_nop 0
	v_pk_add_f32 v[54:55], v[54:55], v[112:113] op_sel:[1,0] op_sel_hi:[0,1]
	v_mov_b32_e32 v57, v54
	v_pk_add_f32 v[114:115], v[56:57], v[116:117] neg_lo:[0,1] neg_hi:[0,1]
	v_mov_b32_e32 v15, v112
	v_sub_f32_e32 v16, v56, v114
	v_pk_add_f32 v[14:15], v[14:15], v[114:115] neg_lo:[0,1] neg_hi:[0,1]
	v_sub_f32_e32 v16, v116, v16
	v_add_f32_e32 v14, v14, v16
	v_add_f32_e32 v14, v14, v15
	v_add_f32_e32 v14, v54, v14
	v_cndmask_b32_e32 v14, v216, v14, vcc
	v_cmp_lt_f32_e64 vcc, |v12|, s64
	s_nop 1
	v_cndmask_b32_e32 v12, v14, v12, vcc
; #define LAS __attribute__((address_space(3)))
; template <int MIX>
; __device__ __forceinline__ void ch_process(const Raw<MIX>& R, const MixPar& par, LAS unsigned char* B, int chunk) {
;     ...
;         LAS float* La = Gt + 64;
;         if (cgi == 0) La[s] = la;
;         __syncthreads();
;         float g = 0.f, ge = 0.f;
; #pragma unroll
;         for (int j = 0; j < 16; ++j) { const float t = La[(s & ~15) + j]; ge += t; g += (j <= pm) ? t : 0.f; }
;         const float eg = expf(g), ew = expf(ge - g);
;         float bb[16], cc[16];
; #pragma unroll
;         for (int i = 0; i < 8; ++i) { bb[i] = b0[i]; bb[8 + i] = b1[i]; cc[i] = c0[i]; cc[8 + i] = c1[i]; }
; #pragma unroll
;         for (int i = 0; i < 4; ++i) { const int cc0 = cgi * 16 + 4 * i;
;             *(LAS u32x2*)(B + C::B_QH + s * C::RS + cc0 * 2) = (u32x2){pkh(cc[4 * i], cc[4 * i + 1]), pkh(cc[4 * i + 2], cc[4 * i + 3])};
;             *(LAS u32x2*)(B + C::B_KH + s * C::RS + cc0 * 2) = (u32x2){pkh(bb[4 * i], bb[4 * i + 1]), pkh(bb[4 * i + 2], bb[4 * i + 3])};
;             *(LAS u32x2*)(B + C::B_QT + s * C::RS + cc0 * 2) = (u32x2){pkh(cc[4 * i] * eg, cc[4 * i + 1] * eg), pkh(cc[4 * i + 2] * eg, cc[4 * i + 3] * eg)};
; #pragma unroll
;             for (int e = 0; e < 4; ++e) *(LAS f16_t*)(B + C::B_KT + (cc0 + e) * C::TS_ + s * 2) = (f16_t)(bb[4 * i + e] * ew); }
; #pragma unroll
;         for (int i = 0; i < 4; ++i) *(LAS f16_t*)(B + C::B_VT + (cgi * 4 + i) * C::TS_ + s * 2) = (f16_t)(x[i] * dt);
;         *(LAS f32x4*)(Lf + RC::OFF_XSD + s * 32 + cgi * 4) = (f32x4){x[0] * dsk, x[1] * dsk, x[2] * dsk, x[3] * dsk};
;         if (cgi == 0) Gt[s] = g;
.LBB0_181:
	s_or_b64 exec, exec, s[4:5]
	v_ashrrev_i32_e32 v14, 3, v13
	v_and_b32_e32 v15, 7, v13
	v_cmp_eq_u32_e32 vcc, 0, v15
	v_lshl_add_u32 v13, v14, 2, 0
	s_and_saveexec_b64 s[4:5], vcc
	v_mul_f32_e64 v16, v12, -v73
	v_add_u32_e32 v54, 0x12700, v13
	ds_write_b32 v54, v16
	s_or_b64 exec, exec, s[4:5]
	v_and_b32_e32 v54, 0x3ffffff0, v14
	v_lshl_add_u32 v54, v54, 2, 0
	v_add_u32_e32 v59, 0x12700, v54
	s_waitcnt lgkmcnt(0)
	s_barrier
	ds_read_b128 v[54:57], v59
	v_and_b32_e32 v16, 15, v14
	v_cmp_ne_u32_e64 s[50:51], 0, v16
	ds_read_b128 v[112:115], v59 offset:16
	ds_read_b128 v[116:119], v59 offset:32
	ds_read_b128 v[120:123], v59 offset:48
	s_waitcnt vmcnt(1)
	v_cvt_f32_f16_sdwa v125, v18 dst_sel:DWORD dst_unused:UNUSED_PAD src0_sel:WORD_1
	s_waitcnt lgkmcnt(3)
	v_add_f32_e32 v54, 0, v54
	v_add_f32_e32 v59, v54, v55
	v_cndmask_b32_e64 v55, 0, v55, s[50:51]
	v_cmp_lt_u32_e64 s[50:51], 1, v16
	v_add_f32_e32 v54, v54, v55
	v_add_f32_e32 v55, v59, v56
	v_cndmask_b32_e64 v56, 0, v56, s[50:51]
	v_cmp_lt_u32_e64 s[50:51], 2, v16
	v_add_f32_e32 v54, v54, v56
	v_add_f32_e32 v55, v55, v57
	v_cndmask_b32_e64 v56, 0, v57, s[50:51]
	v_cmp_lt_u32_e64 s[50:51], 3, v16
	v_add_f32_e32 v54, v54, v56
	s_waitcnt lgkmcnt(2)
	v_add_f32_e32 v55, v55, v112
	v_cndmask_b32_e64 v56, 0, v112, s[50:51]
	v_cmp_lt_u32_e64 s[50:51], 4, v16
	v_add_f32_e32 v54, v54, v56
	v_add_f32_e32 v55, v55, v113
	v_cndmask_b32_e64 v56, 0, v113, s[50:51]
	v_cmp_lt_u32_e64 s[50:51], 5, v16
	v_add_f32_e32 v54, v54, v56
	v_add_f32_e32 v55, v55, v114
	v_cndmask_b32_e64 v56, 0, v114, s[50:51]
	v_cmp_lt_u32_e64 s[50:51], 6, v16
	v_add_f32_e32 v54, v54, v56
	v_add_f32_e32 v55, v55, v115
	v_cndmask_b32_e64 v56, 0, v115, s[50:51]
	v_cmp_lt_u32_e64 s[50:51], 7, v16
	v_add_f32_e32 v54, v54, v56
	s_waitcnt lgkmcnt(1)
	v_add_f32_e32 v55, v55, v116
	v_cndmask_b32_e64 v56, 0, v116, s[50:51]
	v_cmp_lt_u32_e64 s[50:51], 8, v16
	v_add_f32_e32 v54, v54, v56
	v_add_f32_e32 v55, v55, v117
	v_cndmask_b32_e64 v56, 0, v117, s[50:51]
	v_cmp_lt_u32_e64 s[50:51], 9, v16
	v_add_f32_e32 v54, v54, v56
	v_add_f32_e32 v55, v55, v118
	v_cndmask_b32_e64 v56, 0, v118, s[50:51]
	v_cmp_lt_u32_e64 s[50:51], 10, v16
	v_add_f32_e32 v54, v54, v56
	v_add_f32_e32 v55, v55, v119
	v_cndmask_b32_e64 v56, 0, v119, s[50:51]
	v_cmp_lt_u32_e64 s[50:51], 11, v16
	v_add_f32_e32 v54, v54, v56
	s_waitcnt lgkmcnt(0)
	v_add_f32_e32 v55, v55, v120
	v_cndmask_b32_e64 v56, 0, v120, s[50:51]
	v_cmp_lt_u32_e64 s[50:51], 12, v16
	v_add_f32_e32 v54, v54, v56
	v_add_f32_e32 v55, v55, v121
	v_cndmask_b32_e64 v56, 0, v121, s[50:51]
	v_cmp_lt_u32_e64 s[50:51], 13, v16
	v_add_f32_e32 v54, v54, v56
	v_add_f32_e32 v55, v55, v122
	v_cndmask_b32_e64 v56, 0, v122, s[50:51]
	v_cmp_eq_u32_e64 s[50:51], 15, v16
	v_add_f32_e32 v54, v54, v56
	v_add_f32_e32 v55, v55, v123
	v_cndmask_b32_e64 v16, 0, v123, s[50:51]
	v_add_f32_e32 v16, v54, v16
	v_mul_f32_e32 v54, 0x3fb8aa3b, v16
	v_fma_f32 v56, v16, s19, -v54
	v_rndne_f32_e32 v57, v54
	v_fmac_f32_e32 v56, 0x32a5705f, v16
	v_sub_f32_e32 v54, v54, v57
	v_add_f32_e32 v54, v54, v56
	v_exp_f32_e32 v54, v54
	v_cvt_i32_f32_e32 v56, v57
	v_sub_f32_e32 v55, v55, v16
	v_cmp_ngt_f32_e64 s[50:51], s96, v16
	v_cvt_f32_f16_e32 v124, v18
	v_ldexp_f32 v54, v54, v56
	v_mul_f32_e32 v56, 0x3fb8aa3b, v55
	v_fma_f32 v57, v55, s19, -v56
	v_rndne_f32_e32 v59, v56
	v_fmac_f32_e32 v57, 0x32a5705f, v55
	v_sub_f32_e32 v56, v56, v59
	v_add_f32_e32 v56, v56, v57
	v_exp_f32_e32 v56, v56
	v_cvt_i32_f32_e32 v57, v59
	v_cndmask_b32_e64 v54, 0, v54, s[50:51]
	v_cmp_nlt_f32_e64 s[50:51], s97, v16
	v_cvt_f32_f16_sdwa v127, v19 dst_sel:DWORD dst_unused:UNUSED_PAD src0_sel:WORD_1
	v_cvt_f32_f16_e32 v126, v19
	v_cndmask_b32_e64 v54, v216, v54, s[50:51]
	v_ldexp_f32 v56, v56, v57
	v_cmp_ngt_f32_e64 s[50:51], s96, v55
	s_movk_i32 s2, 0xfef2
	v_cvt_f32_f16_sdwa v129, v20 dst_sel:DWORD dst_unused:UNUSED_PAD src0_sel:WORD_1
	v_cndmask_b32_e64 v56, 0, v56, s[50:51]
	v_cmp_nlt_f32_e64 s[50:51], s97, v55
	v_mul_lo_u32 v55, v14, s11
	v_pk_mul_f32 v[114:115], v[54:55], v[124:125] op_sel_hi:[0,1]
	v_cndmask_b32_e64 v59, v216, v56, s[50:51]
	v_add_u32_e32 v56, 0, v55
	v_mad_u64_u32 v[112:113], s[2:3], v14, s2, v[56:57]
	v_pk_mul_f32 v[116:117], v[54:55], v[126:127] op_sel_hi:[0,1]
	s_movk_i32 s2, 0x900
	v_lshl_add_u32 v119, v15, 5, v56
	v_cvt_pk_f16_f32 v114, v114, v115
	v_cvt_pk_f16_f32 v115, v116, v117
	v_fma_mixlo_f16 v55, v59, v0, 0 op_sel_hi:[0,1,0]
	v_mad_u32_u24 v116, v15, s2, v112
	v_cvt_f32_f16_e32 v128, v20
	v_cvt_f32_f16_sdwa v131, v21 dst_sel:DWORD dst_unused:UNUSED_PAD src0_sel:WORD_1
	v_cvt_f32_f16_e32 v130, v21
	ds_write_b64 v119, v[18:19]
	ds_write_b64 v119, v[0:1] offset:17408
	ds_write_b64 v119, v[114:115] offset:34816
	ds_write_b16 v116, v55 offset:52224
	v_fma_mixlo_f16 v55, v59, v0, 0 op_sel:[0,1,0] op_sel_hi:[0,1,0]
	ds_write_b16 v116, v55 offset:52368
	v_fma_mixlo_f16 v55, v59, v1, 0 op_sel_hi:[0,1,0]
	v_lshlrev_b32_e32 v111, 4, v15
	ds_write_b16 v116, v55 offset:52512
	v_fma_mixlo_f16 v55, v59, v1, 0 op_sel:[0,1,0] op_sel_hi:[0,1,0]
	ds_write_b16 v116, v55 offset:52656
	v_or_b32_e32 v55, 4, v111
	v_lshl_add_u32 v113, v55, 1, v56
	v_pk_mul_f32 v[56:57], v[54:55], v[128:129] op_sel_hi:[0,1]
	v_pk_mul_f32 v[114:115], v[54:55], v[130:131] op_sel_hi:[0,1]
	v_cvt_f32_f16_sdwa v133, v4 dst_sel:DWORD dst_unused:UNUSED_PAD src0_sel:WORD_1
	v_cvt_f32_f16_e32 v132, v4
	v_cvt_f32_f16_sdwa v135, v5 dst_sel:DWORD dst_unused:UNUSED_PAD src0_sel:WORD_1
	v_cvt_f32_f16_e32 v134, v5
	v_cvt_pk_f16_f32 v56, v56, v57
	v_cvt_pk_f16_f32 v57, v114, v115
	ds_write_b64 v113, v[56:57] offset:34816
	v_fma_mixlo_f16 v56, v59, v2, 0 op_sel_hi:[0,1,0]
; #define LAS __attribute__((address_space(3)))
; __device__ __forceinline__ float hload(const f16_t* p) { return (float)(*p); }
; template <int MIX, bool SAMPLE>
; __device__ __forceinline__ void rec_load(Raw<MIX>& R, const f16_t* proj, int chunk, int sg, int head, int vcol0) {
;     ...
;     } else {
;         const f16_t* pb = rowp + C_SXBC + 256 + (head >> 1) * 128 + cgi * 16;
;         R.b[0] = *(const u32x4*)pb; R.b[1] = *(const u32x4*)(pb + 8); R.c[0] = *(const u32x4*)(pb + 256); R.c[1] = *(const u32x4*)(pb + 264);
;         R.x = *(const u32x2*)(rowp + C_SXBC + head * 64 + vcol0 + cgi * 4);
;         R.dt = hload(rowp + C_SDT + head);
;     }
; template <int MIX>
; __device__ __forceinline__ void ch_process(const Raw<MIX>& R, const MixPar& par, LAS unsigned char* B, int chunk) {
;     ...
;         for (int i = 0; i < 4; ++i) { const int cc0 = cgi * 16 + 4 * i;
;             *(LAS u32x2*)(B + C::B_QH + s * C::RS + cc0 * 2) = (u32x2){pkh(cc[4 * i], cc[4 * i + 1]), pkh(cc[4 * i + 2], cc[4 * i + 3])};
;             *(LAS u32x2*)(B + C::B_KH + s * C::RS + cc0 * 2) = (u32x2){pkh(bb[4 * i], bb[4 * i + 1]), pkh(bb[4 * i + 2], bb[4 * i + 3])};
;             *(LAS u32x2*)(B + C::B_QT + s * C::RS + cc0 * 2) = (u32x2){pkh(cc[4 * i] * eg, cc[4 * i + 1] * eg), pkh(cc[4 * i + 2] * eg, cc[4 * i + 3] * eg)};
; #pragma unroll
;             for (int e = 0; e < 4; ++e) *(LAS f16_t*)(B + C::B_KT + (cc0 + e) * C::TS_ + s * 2) = (f16_t)(bb[4 * i + e] * ew); }
; #pragma unroll
;         for (int i = 0; i < 4; ++i) *(LAS f16_t*)(B + C::B_VT + (cgi * 4 + i) * C::TS_ + s * 2) = (f16_t)(x[i] * dt);
;         *(LAS f32x4*)(Lf + RC::OFF_XSD + s * 32 + cgi * 4) = (f32x4){x[0] * dsk, x[1] * dsk, x[2] * dsk, x[3] * dsk};
;         if (cgi == 0) Gt[s] = g;
	v_mad_u32_u24 v114, v55, s28, v112
	v_fma_mixlo_f16 v55, v59, v2, 0 op_sel:[0,1,0] op_sel_hi:[0,1,0]
	ds_write2st64_b64 v113, v[20:21], v[2:3] offset1:34
	ds_write_b16 v114, v56 offset:52224
	ds_write_b16 v116, v55 offset:52944
	v_fma_mixlo_f16 v55, v59, v3, 0 op_sel_hi:[0,1,0]
	ds_write_b16 v116, v55 offset:53088
	v_fma_mixlo_f16 v55, v59, v3, 0 op_sel:[0,1,0] op_sel_hi:[0,1,0]
	v_pk_mul_f32 v[56:57], v[54:55], v[132:133] op_sel_hi:[0,1]
	v_pk_mul_f32 v[112:113], v[54:55], v[134:135] op_sel_hi:[0,1]
	v_cvt_f32_f16_sdwa v137, v6 dst_sel:DWORD dst_unused:UNUSED_PAD src0_sel:WORD_1
	v_cvt_f32_f16_e32 v136, v6
	v_cvt_f32_f16_sdwa v141, v7 dst_sel:DWORD dst_unused:UNUSED_PAD src0_sel:WORD_1
	v_cvt_f32_f16_e32 v140, v7
	ds_write_b16 v116, v55 offset:53232
	ds_write_b64 v119, v[4:5] offset:16
	ds_write_b64 v119, v[8:9] offset:17424
	v_cvt_pk_f16_f32 v56, v56, v57
	v_cvt_pk_f16_f32 v57, v112, v113
	v_fma_mixlo_f16 v55, v59, v8, 0 op_sel_hi:[0,1,0]
	ds_write_b64 v119, v[56:57] offset:34832
	ds_write_b16 v114, v55 offset:52800
	v_fma_mixlo_f16 v55, v59, v8, 0 op_sel:[0,1,0] op_sel_hi:[0,1,0]
	ds_write_b16 v116, v55 offset:53520
	v_fma_mixlo_f16 v55, v59, v9, 0 op_sel_hi:[0,1,0]
	ds_write_b16 v116, v55 offset:53664
	v_fma_mixlo_f16 v55, v59, v9, 0 op_sel:[0,1,0] op_sel_hi:[0,1,0]
	ds_write_b16 v116, v55 offset:53808
	ds_write_b64 v119, v[6:7] offset:24
	ds_write_b64 v119, v[10:11] offset:17432
	v_pk_mul_f32 v[56:57], v[54:55], v[136:137] op_sel_hi:[0,1]
	v_pk_mul_f32 v[54:55], v[54:55], v[140:141] op_sel_hi:[0,1]
	v_cvt_pk_f16_f32 v56, v56, v57
	v_cvt_pk_f16_f32 v57, v54, v55
	v_fma_mixlo_f16 v54, v59, v10, 0 op_sel_hi:[0,1,0]
	ds_write_b64 v119, v[56:57] offset:34840
	ds_write_b16 v114, v54 offset:53376
	v_fma_mixlo_f16 v54, v59, v10, 0 op_sel:[0,1,0] op_sel_hi:[0,1,0]
	ds_write_b16 v116, v54 offset:54096
	v_fma_mixlo_f16 v54, v59, v11, 0 op_sel_hi:[0,1,0]
	v_lshlrev_b32_e32 v118, 1, v14
	ds_write_b16 v116, v54 offset:54240
	v_fma_mixlo_f16 v54, v59, v11, 0 op_sel:[0,1,0] op_sel_hi:[0,1,0]
	v_mul_u32_u24_e32 v15, 0x240, v15
	s_waitcnt vmcnt(0)
	v_cvt_f32_f16_sdwa v143, v60 dst_sel:DWORD dst_unused:UNUSED_PAD src0_sel:WORD_1
	v_cvt_f32_f16_e32 v142, v60
	v_cvt_f32_f16_sdwa v145, v61 dst_sel:DWORD dst_unused:UNUSED_PAD src0_sel:WORD_1
	v_cvt_f32_f16_e32 v144, v61
	ds_write_b16 v116, v54 offset:54384
	v_fma_mixlo_f16 v54, v12, v60, 0 op_sel_hi:[0,1,0]
	v_add3_u32 v15, s24, v118, v15
	ds_write_b16 v15, v54
	v_fma_mixlo_f16 v54, v12, v60, 0 op_sel:[0,1,0] op_sel_hi:[0,1,0]
	ds_write_b16 v15, v54 offset:144
	v_fma_mixlo_f16 v54, v12, v61, 0 op_sel_hi:[0,1,0]
	v_fma_mixlo_f16 v12, v12, v61, 0 op_sel:[0,1,0] op_sel_hi:[0,1,0]
	ds_write_b16 v15, v12 offset:432
	v_mov_b32_e32 v59, v58
	v_lshlrev_b32_e32 v12, 7, v14
	ds_write_b16 v15, v54 offset:288
	v_pk_mul_f32 v[56:57], v[58:59], v[144:145]
	v_pk_mul_f32 v[54:55], v[62:63], v[142:143]
	v_add3_u32 v12, s29, v12, v111
	ds_write_b128 v12, v[54:57]
	s_and_saveexec_b64 s[4:5], vcc
	v_add_u32_e32 v12, 0x12600, v13
	ds_write_b32 v12, v16
	s_or_b64 exec, exec, s[4:5]
	s_cmpk_eq_i32 s8, 0x7c0
	s_waitcnt lgkmcnt(0)
	s_barrier
	s_cbranch_scc1 .LBB0_187
	v_mov_b32_e32 v0, v202
	s_add_i32 s2, s7, s8
	v_ashrrev_i32_e32 v1, 3, v0
	v_and_b32_e32 v6, 7, v0
	v_add3_u32 v2, s2, v1, 64
	v_mov_b64_e32 v[0:1], s[54:55]
	v_mad_i64_i32 v[0:1], s[2:3], v2, s18, v[0:1]
	s_mov_b32 s59, s79
	v_lshl_add_u64 v[2:3], v[0:1], 0, s[58:59]
	v_lshlrev_b32_e32 v16, 5, v6
	s_lshl_b32 s78, s83, 1
	v_lshl_add_u64 v[2:3], v[2:3], 0, v[16:17]
	v_lshl_add_u64 v[4:5], v[0:1], 0, s[78:79]
	s_lshl_b32 s78, s82, 1
	v_lshl_add_u64 v[12:13], v[2:3], 0, s[60:61]
	v_add_co_u32_e32 v2, vcc, 0x1000, v2
	v_lshl_add_u64 v[4:5], v[4:5], 0, s[78:79]
	v_lshlrev_b32_e32 v16, 3, v6
	v_addc_co_u32_e32 v3, vcc, 0, v3, vcc
	v_lshl_add_u64 v[4:5], v[4:5], 0, v[16:17]
	v_add_co_u32_e32 v4, vcc, 0x1000, v4
	s_lshl_b32 s78, s30, 1
	s_nop 0
	v_addc_co_u32_e32 v5, vcc, 0, v5, vcc
	v_lshl_add_u64 v[0:1], v[0:1], 0, s[78:79]
	v_add_co_u32_e32 v0, vcc, 0x2000, v0
	s_nop 1
	v_addc_co_u32_e32 v1, vcc, 0, v1, vcc
	global_load_dwordx2 v[60:61], v[4:5], off offset:2576
	global_load_ushort v75, v[0:1], off offset:16
	s_nop 0
	global_load_dwordx4 v[0:3], v[2:3], off offset:3088
	s_nop 0
	global_load_dwordx4 v[4:7], v[12:13], off offset:528
	global_load_dwordx4 v[8:11], v[12:13], off offset:16
	global_load_dwordx4 v[18:21], v[12:13], off offset:512
; template <int MIX>
; __device__ __forceinline__ void ch_scan(f32x4 (&St)[ChCfg<MIX>::K / 16], LAS unsigned char* B, int vg, int lane) {
;     typedef ChCfg<MIX> C; typedef RecCfg<MIX> RC; constexpr int K = C::K;
;     const int r = lane & 15, h = lane >> 4;
;     const LAS float* Gt = (const LAS float*)(B + C::B_G);
;     LAS float* Of = (LAS float*)B + RC::OFF_O;
; #pragma unroll
;     for (int mc = 0; mc < 4; ++mc) {
;         const int t0 = mc * 16;
;         f32x4 X = (f32x4){0.f, 0.f, 0.f, 0.f};
; #pragma unroll
;         for (int kb = 0; kb < K / 32; ++kb) {
;             const f16x8 a = *(const LAS f16x8*)(B + C::B_KH + (t0 + r) * C::RS + (kb * 32 + 8 * h) * 2);
;             const f16x8 b = *(const LAS f16x8*)(B + C::B_QH + (t0 + r) * C::RS + (kb * 32 + 8 * h) * 2);
;             X = __builtin_amdgcn_mfma_f32_16x16x32_f16(a, b, X, 0, 0, 0); }
;         const float gi = Gt[t0 + r]; const f32x4 gj = *(const LAS f32x4*)(Gt + t0 + 4 * h);
;         f16x8 pa, vb;
; #pragma unroll
;         for (int e = 0; e < 4; ++e) { const float d = fminf(gi - gj[e], 0.f); const float pv = (4 * h + e <= r) ? X[e] * __expf(d) : 0.f; pa[e] = (f16_t)pv; pa[4 + e] = (f16_t)0.f; }
;         { const u32x2 vv = *(const LAS u32x2*)(B + C::B_VT + (16 * vg + r) * C::TS_ + (t0 + 4 * h) * 2);
;           const u32x4 v4 = (u32x4){vv.x, vv.y, 0u, 0u}; vb = __builtin_bit_cast(f16x8, v4); }
;         f32x4 O = __builtin_amdgcn_mfma_f32_16x16x32_f16(pa, vb, (f32x4){0.f, 0.f, 0.f, 0.f}, 0, 0, 0);
; #pragma unroll
;         for (int m = 0; m < K / 32; ++m) {
;             const u32x2 qa0 = *(const LAS u32x2*)(B + C::B_QT + (t0 + r) * C::RS + (32 * m + 4 * h) * 2), qa1 = *(const LAS u32x2*)(B + C::B_QT + (t0 + r) * C::RS + (32 * m + 16 + 4 * h) * 2);
;             const u32x4 qa4 = (u32x4){qa0.x, qa0.y, qa1.x, qa1.y};
;             const u32x4 sb4 = (u32x4){pkh(St[2 * m][0], St[2 * m][1]), pkh(St[2 * m][2], St[2 * m][3]), pkh(St[2 * m + 1][0], St[2 * m + 1][1]), pkh(St[2 * m + 1][2], St[2 * m + 1][3])};
;             O = __builtin_amdgcn_mfma_f32_16x16x32_f16(__builtin_bit_cast(f16x8, qa4), __builtin_bit_cast(f16x8, sb4), O, 0, 0, 0); }
; #pragma unroll
;         for (int e = 0; e < 4; ++e) Of[(t0 + 4 * h + e) * 32 + 16 * vg + r] = O[e];
;         const float ge = __expf(Gt[t0 + 15]);
; #pragma unroll
;         for (int kt = 0; kt < K / 16; ++kt) {
.LBB0_187:
	s_andn2_b64 vcc, exec, s[56:57]
	s_cbranch_vccnz .LBB0_178
	v_mov_b32_e32 v192, 0
	v_mov_b32_e32 v193, 0
	v_mov_b32_e32 v196, 0
	v_mov_b32_e32 v197, 0
	v_mov_b32_e32 v200, 0
	v_mov_b32_e32 v201, 0
	v_mov_b32_e32 v232, 0
	v_mov_b32_e32 v233, 0
	v_mov_b32_e32 v236, 0
	v_mov_b32_e32 v237, 0
	v_mov_b32_e32 v240, 0
	v_mov_b32_e32 v241, 0
	v_mov_b32_e32 v244, 0
	v_mov_b32_e32 v245, 0
	v_add_u32_e32 v59, v71, v76
	ds_read_b128 v[12:15], v91 offset:17408
	ds_read_b128 v[54:57], v91
	ds_read_b128 v[146:149], v91 offset:17472
	ds_read_b128 v[150:153], v91 offset:64
	ds_read_b128 v[154:157], v91 offset:17536
	ds_read_b128 v[158:161], v91 offset:128
	ds_read_b128 v[162:165], v91 offset:17600
	ds_read_b128 v[166:169], v91 offset:192
	ds_read_b32 v16, v70
	ds_read_b128 v[170:173], v74
	v_cvt_pk_f16_f32 v116, v22, v23
	v_cvt_pk_f16_f32 v117, v24, v25
	v_cvt_pk_f16_f32 v118, v50, v51
	v_cvt_pk_f16_f32 v119, v52, v53
	s_waitcnt lgkmcnt(8)
	v_mfma_f32_16x16x32_f16 v[12:15], v[12:15], v[54:57], 0
	v_add_u32_e32 v247, 0x8800, v92
	ds_read2_b64 v[174:177], v247 offset1:4
	ds_read2_b64 v[178:181], v247 offset0:8 offset1:12
	ds_read2_b64 v[182:185], v247 offset0:16 offset1:20
	ds_read2_b64 v[186:189], v247 offset0:24 offset1:28
	v_add_u32_e32 v248, v72, v69
	ds_read_b64 v[242:243], v248
	s_waitcnt lgkmcnt(11)
	v_mfma_f32_16x16x32_f16 v[12:15], v[146:149], v[150:153], v[12:15]
	s_waitcnt lgkmcnt(9)
	v_mfma_f32_16x16x32_f16 v[12:15], v[154:157], v[158:161], v[12:15]
	s_waitcnt lgkmcnt(7)
	v_mfma_f32_16x16x32_f16 v[12:15], v[162:165], v[166:169], v[12:15]
	s_waitcnt lgkmcnt(5)
	v_sub_f32_e32 v54, v16, v170
	v_min_f32_e32 v54, 0, v54
	v_mul_f32_e32 v54, 0x3fb8aa3b, v54
	v_exp_f32_e32 v54, v54
	s_nop 0
	s_nop 1
	v_fma_mixlo_f16 v12, v12, v54, 0
	v_sub_f32_e32 v54, v16, v171
	v_min_f32_e32 v54, 0, v54
	v_mul_f32_e32 v54, 0x3fb8aa3b, v54
	v_exp_f32_e32 v54, v54
	v_cndmask_b32_e64 v12, v12, 0, s[42:43]
	v_fma_mixlo_f16 v13, v13, v54, 0
	v_sub_f32_e32 v54, v16, v172
	v_sub_f32_e32 v16, v16, v173
	v_min_f32_e32 v54, 0, v54
	v_min_f32_e32 v16, 0, v16
	v_mul_f32_e32 v54, 0x3fb8aa3b, v54
	v_mul_f32_e32 v16, 0x3fb8aa3b, v16
	v_exp_f32_e32 v54, v54
	v_exp_f32_e32 v16, v16
	v_cndmask_b32_e64 v13, 0, v13, s[44:45]
	v_mov_b32_e32 v56, v17
	v_fma_mixlo_f16 v14, v14, v54, 0
	v_fma_mixlo_f16 v15, v15, v16, 0
	v_cndmask_b32_e64 v14, v14, 0, s[46:47]
	v_cndmask_b32_e64 v15, v15, 0, s[48:49]
	v_pack_b32_f16 v15, v14, v15
	v_pack_b32_f16 v14, v12, v13
	v_mov_b32_e32 v246, s10
	ds_read_b32 v246, v246
	v_add_u32_e32 v249, v71, v68
	ds_read2st64_b64 v[112:115], v249 offset0:102 offset1:120
	ds_read_b64 v[190:191], v59 offset:52224
	ds_read_b64 v[194:195], v59 offset:54528
	v_add_u32_e32 v250, v71, v77
	ds_read_b64 v[198:199], v250 offset:52224
	ds_read_b64 v[230:231], v249 offset:63744
	ds_read_b64 v[234:235], v95 offset:13824
	v_add_u32_e32 v251, v71, v78
	ds_read_b64 v[238:239], v251 offset:52224
	v_mov_b32_e32 v16, v17
	v_mov_b32_e32 v57, v17
	s_nop 0
	s_waitcnt lgkmcnt(8)
	v_mfma_f32_16x16x32_f16 v[12:15], v[14:17], v[242:245], 0
	s_nop 0
	v_mfma_f32_16x16x32_f16 v[12:15], v[174:177], v[116:119], v[12:15]
	v_cvt_pk_f16_f32 v116, v46, v47
	v_cvt_pk_f16_f32 v117, v48, v49
	v_cvt_pk_f16_f32 v118, v42, v43
	v_cvt_pk_f16_f32 v119, v44, v45
	s_nop 0
	s_nop 0
	v_mfma_f32_16x16x32_f16 v[12:15], v[178:181], v[116:119], v[12:15]
	v_cvt_pk_f16_f32 v116, v38, v39
	v_cvt_pk_f16_f32 v117, v40, v41
	v_cvt_pk_f16_f32 v118, v34, v35
	v_cvt_pk_f16_f32 v119, v36, v37
	s_nop 0
	s_nop 0
	v_mfma_f32_16x16x32_f16 v[12:15], v[182:185], v[116:119], v[12:15]
	v_cvt_pk_f16_f32 v116, v30, v31
	v_cvt_pk_f16_f32 v117, v32, v33
	v_cvt_pk_f16_f32 v118, v26, v27
	v_cvt_pk_f16_f32 v119, v28, v29
	v_mov_b32_e32 v16, v17
	s_nop 0
	v_mfma_f32_16x16x32_f16 v[12:15], v[186:189], v[116:119], v[12:15]
	s_nop 7
	ds_write2_b32 v93, v12, v13 offset1:32
	ds_write_b32 v93, v14 offset:256
	ds_write_b32 v94, v15
	s_waitcnt lgkmcnt(10)
	v_mul_f32_e32 v12, 0x3fb8aa3b, v246
	v_exp_f32_e32 v12, v12
	s_waitcnt lgkmcnt(9)
	v_mov_b32_e32 v14, v112
	v_mov_b32_e32 v15, v113
	v_pk_mul_f32 v[24:25], v[24:25], v[12:13] op_sel_hi:[1,0]
	v_pk_mul_f32 v[22:23], v[22:23], v[12:13] op_sel_hi:[1,0]
	v_pk_mul_f32 v[52:53], v[52:53], v[12:13] op_sel_hi:[1,0]
	v_pk_mul_f32 v[50:51], v[50:51], v[12:13] op_sel_hi:[1,0]
	v_mfma_f32_16x16x32_f16 v[22:25], v[14:17], v[242:245], v[22:25]
	v_pk_mul_f32 v[48:49], v[48:49], v[12:13] op_sel_hi:[1,0]
	v_pk_mul_f32 v[46:47], v[46:47], v[12:13] op_sel_hi:[1,0]
	s_waitcnt lgkmcnt(8)
	v_mfma_f32_16x16x32_f16 v[50:53], v[190:193], v[242:245], v[50:53]
	v_pk_mul_f32 v[44:45], v[44:45], v[12:13] op_sel_hi:[1,0]
	v_pk_mul_f32 v[42:43], v[42:43], v[12:13] op_sel_hi:[1,0]
	s_waitcnt lgkmcnt(7)
	v_mfma_f32_16x16x32_f16 v[46:49], v[194:197], v[242:245], v[46:49]
	v_pk_mul_f32 v[40:41], v[40:41], v[12:13] op_sel_hi:[1,0]
	s_waitcnt lgkmcnt(6)
	v_mfma_f32_16x16x32_f16 v[42:45], v[198:201], v[242:245], v[42:45]
	v_mov_b32_e32 v14, v114
	v_mov_b32_e32 v15, v115
	v_pk_mul_f32 v[38:39], v[38:39], v[12:13] op_sel_hi:[1,0]
	v_pk_mul_f32 v[36:37], v[36:37], v[12:13] op_sel_hi:[1,0]
	v_pk_mul_f32 v[34:35], v[34:35], v[12:13] op_sel_hi:[1,0]
	v_mfma_f32_16x16x32_f16 v[38:41], v[14:17], v[242:245], v[38:41]
	v_pk_mul_f32 v[32:33], v[32:33], v[12:13] op_sel_hi:[1,0]
	v_pk_mul_f32 v[30:31], v[30:31], v[12:13] op_sel_hi:[1,0]
	s_waitcnt lgkmcnt(5)
	v_mfma_f32_16x16x32_f16 v[34:37], v[230:233], v[242:245], v[34:37]
	v_pk_mul_f32 v[28:29], v[28:29], v[12:13] op_sel_hi:[1,0]
	s_waitcnt lgkmcnt(4)
	v_mfma_f32_16x16x32_f16 v[30:33], v[234:237], v[242:245], v[30:33]
	v_pk_mul_f32 v[26:27], v[26:27], v[12:13] op_sel_hi:[1,0]
	v_cvt_pk_f16_f32 v116, v22, v23
	v_cvt_pk_f16_f32 v117, v24, v25
	s_waitcnt lgkmcnt(3)
; template <int MIX>
; __device__ __forceinline__ void ch_scan(f32x4 (&St)[ChCfg<MIX>::K / 16], LAS unsigned char* B, int vg, int lane) {
;     typedef ChCfg<MIX> C; typedef RecCfg<MIX> RC; constexpr int K = C::K;
;     const int r = lane & 15, h = lane >> 4;
;     const LAS float* Gt = (const LAS float*)(B + C::B_G);
;     LAS float* Of = (LAS float*)B + RC::OFF_O;
; #pragma unroll
;     for (int mc = 0; mc < 4; ++mc) {
;         const int t0 = mc * 16;
;         f32x4 X = (f32x4){0.f, 0.f, 0.f, 0.f};
; #pragma unroll
;         for (int kb = 0; kb < K / 32; ++kb) {
;             const f16x8 a = *(const LAS f16x8*)(B + C::B_KH + (t0 + r) * C::RS + (kb * 32 + 8 * h) * 2);
;             const f16x8 b = *(const LAS f16x8*)(B + C::B_QH + (t0 + r) * C::RS + (kb * 32 + 8 * h) * 2);
;             X = __builtin_amdgcn_mfma_f32_16x16x32_f16(a, b, X, 0, 0, 0); }
;         const float gi = Gt[t0 + r]; const f32x4 gj = *(const LAS f32x4*)(Gt + t0 + 4 * h);
;         f16x8 pa, vb;
; #pragma unroll
;         for (int e = 0; e < 4; ++e) { const float d = fminf(gi - gj[e], 0.f); const float pv = (4 * h + e <= r) ? X[e] * __expf(d) : 0.f; pa[e] = (f16_t)pv; pa[4 + e] = (f16_t)0.f; }
;         { const u32x2 vv = *(const LAS u32x2*)(B + C::B_VT + (16 * vg + r) * C::TS_ + (t0 + 4 * h) * 2);
;           const u32x4 v4 = (u32x4){vv.x, vv.y, 0u, 0u}; vb = __builtin_bit_cast(f16x8, v4); }
;         f32x4 O = __builtin_amdgcn_mfma_f32_16x16x32_f16(pa, vb, (f32x4){0.f, 0.f, 0.f, 0.f}, 0, 0, 0);
; #pragma unroll
;         for (int m = 0; m < K / 32; ++m) {
;             const u32x2 qa0 = *(const LAS u32x2*)(B + C::B_QT + (t0 + r) * C::RS + (32 * m + 4 * h) * 2), qa1 = *(const LAS u32x2*)(B + C::B_QT + (t0 + r) * C::RS + (32 * m + 16 + 4 * h) * 2);
;             const u32x4 qa4 = (u32x4){qa0.x, qa0.y, qa1.x, qa1.y};
;             const u32x4 sb4 = (u32x4){pkh(St[2 * m][0], St[2 * m][1]), pkh(St[2 * m][2], St[2 * m][3]), pkh(St[2 * m + 1][0], St[2 * m + 1][1]), pkh(St[2 * m + 1][2], St[2 * m + 1][3])};
;             O = __builtin_amdgcn_mfma_f32_16x16x32_f16(__builtin_bit_cast(f16x8, qa4), __builtin_bit_cast(f16x8, sb4), O, 0, 0, 0); }
; #pragma unroll
;         for (int e = 0; e < 4; ++e) Of[(t0 + 4 * h + e) * 32 + 16 * vg + r] = O[e];
;         const float ge = __expf(Gt[t0 + 15]);
; #pragma unroll
;         for (int kt = 0; kt < K / 16; ++kt) {
	v_mfma_f32_16x16x32_f16 v[26:29], v[238:241], v[242:245], v[26:29]
	v_add_u32_e32 v59, v82, v76
	ds_read_b128 v[12:15], v96 offset:17408
	ds_read_b128 v[54:57], v96
	ds_read_b128 v[146:149], v96 offset:17472
	ds_read_b128 v[150:153], v96 offset:64
	ds_read_b128 v[154:157], v96 offset:17536
	ds_read_b128 v[158:161], v96 offset:128
	ds_read_b128 v[162:165], v96 offset:17600
	ds_read_b128 v[166:169], v96 offset:192
	ds_read_b32 v16, v79
	ds_read_b128 v[170:173], v80
	v_cvt_pk_f16_f32 v118, v50, v51
	v_cvt_pk_f16_f32 v119, v52, v53
	s_waitcnt lgkmcnt(8)
	v_mfma_f32_16x16x32_f16 v[12:15], v[12:15], v[54:57], 0
	v_add_u32_e32 v247, 0x8800, v97
	ds_read2_b64 v[174:177], v247 offset1:4
	ds_read2_b64 v[178:181], v247 offset0:8 offset1:12
	ds_read2_b64 v[182:185], v247 offset0:16 offset1:20
	ds_read2_b64 v[186:189], v247 offset0:24 offset1:28
	v_add_u32_e32 v248, v72, v81
	ds_read_b64 v[242:243], v248
	s_waitcnt lgkmcnt(11)
	v_mfma_f32_16x16x32_f16 v[12:15], v[146:149], v[150:153], v[12:15]
	s_waitcnt lgkmcnt(9)
	v_mfma_f32_16x16x32_f16 v[12:15], v[154:157], v[158:161], v[12:15]
	s_waitcnt lgkmcnt(7)
	v_mfma_f32_16x16x32_f16 v[12:15], v[162:165], v[166:169], v[12:15]
	s_waitcnt lgkmcnt(5)
	v_sub_f32_e32 v54, v16, v170
	v_min_f32_e32 v54, 0, v54
	v_mul_f32_e32 v54, 0x3fb8aa3b, v54
	v_exp_f32_e32 v54, v54
	s_nop 0
	s_nop 1
	v_fma_mixlo_f16 v12, v12, v54, 0
	v_sub_f32_e32 v54, v16, v171
	v_min_f32_e32 v54, 0, v54
	v_mul_f32_e32 v54, 0x3fb8aa3b, v54
	v_exp_f32_e32 v54, v54
	v_cndmask_b32_e64 v12, v12, 0, s[42:43]
	v_fma_mixlo_f16 v13, v13, v54, 0
	v_sub_f32_e32 v54, v16, v172
	v_sub_f32_e32 v16, v16, v173
	v_min_f32_e32 v54, 0, v54
	v_min_f32_e32 v16, 0, v16
	v_mul_f32_e32 v54, 0x3fb8aa3b, v54
	v_mul_f32_e32 v16, 0x3fb8aa3b, v16
	v_exp_f32_e32 v54, v54
	v_exp_f32_e32 v16, v16
	v_cndmask_b32_e64 v13, 0, v13, s[44:45]
	v_mov_b32_e32 v56, v17
	v_fma_mixlo_f16 v14, v14, v54, 0
	v_fma_mixlo_f16 v15, v15, v16, 0
	v_cndmask_b32_e64 v14, v14, 0, s[46:47]
	v_cndmask_b32_e64 v15, v15, 0, s[48:49]
	v_pack_b32_f16 v15, v14, v15
	v_pack_b32_f16 v14, v12, v13
	v_mov_b32_e32 v246, s12
	ds_read_b32 v246, v246
	v_add_u32_e32 v249, v82, v68
	ds_read2st64_b64 v[112:115], v249 offset0:102 offset1:120
	ds_read_b64 v[190:191], v59 offset:52224
	ds_read_b64 v[194:195], v59 offset:54528
	v_add_u32_e32 v250, v82, v77
	ds_read_b64 v[198:199], v250 offset:52224
	ds_read_b64 v[230:231], v249 offset:63744
	ds_read_b64 v[234:235], v100 offset:13824
	v_add_u32_e32 v251, v82, v78
	ds_read_b64 v[238:239], v251 offset:52224
	v_mov_b32_e32 v16, v17
	v_mov_b32_e32 v57, v17
	s_nop 0
	s_waitcnt lgkmcnt(8)
	v_mfma_f32_16x16x32_f16 v[12:15], v[14:17], v[242:245], 0
	s_nop 0
	v_mfma_f32_16x16x32_f16 v[12:15], v[174:177], v[116:119], v[12:15]
	v_cvt_pk_f16_f32 v116, v46, v47
	v_cvt_pk_f16_f32 v117, v48, v49
	v_cvt_pk_f16_f32 v118, v42, v43
	v_cvt_pk_f16_f32 v119, v44, v45
	s_nop 0
	s_nop 0
	v_mfma_f32_16x16x32_f16 v[12:15], v[178:181], v[116:119], v[12:15]
	v_cvt_pk_f16_f32 v116, v38, v39
	v_cvt_pk_f16_f32 v117, v40, v41
	v_cvt_pk_f16_f32 v118, v34, v35
	v_cvt_pk_f16_f32 v119, v36, v37
	s_nop 0
	s_nop 0
	v_mfma_f32_16x16x32_f16 v[12:15], v[182:185], v[116:119], v[12:15]
	v_cvt_pk_f16_f32 v116, v30, v31
	v_cvt_pk_f16_f32 v117, v32, v33
	v_cvt_pk_f16_f32 v118, v26, v27
	v_cvt_pk_f16_f32 v119, v28, v29
	v_mov_b32_e32 v16, v17
	s_nop 0
	v_mfma_f32_16x16x32_f16 v[12:15], v[186:189], v[116:119], v[12:15]
	s_nop 7
	ds_write_b32 v98, v12
	v_add_u32_e32 v12, 0x800, v93
	ds_write2_b32 v12, v13, v14 offset0:32 offset1:64
	ds_write_b32 v99, v15
	s_waitcnt lgkmcnt(10)
	v_mul_f32_e32 v12, 0x3fb8aa3b, v246
	v_exp_f32_e32 v12, v12
	s_waitcnt lgkmcnt(9)
	v_mov_b32_e32 v14, v112
	v_mov_b32_e32 v15, v113
	v_pk_mul_f32 v[24:25], v[24:25], v[12:13] op_sel_hi:[1,0]
	v_pk_mul_f32 v[22:23], v[22:23], v[12:13] op_sel_hi:[1,0]
	v_pk_mul_f32 v[52:53], v[52:53], v[12:13] op_sel_hi:[1,0]
	v_pk_mul_f32 v[50:51], v[50:51], v[12:13] op_sel_hi:[1,0]
	v_mfma_f32_16x16x32_f16 v[22:25], v[14:17], v[242:245], v[22:25]
	v_pk_mul_f32 v[48:49], v[48:49], v[12:13] op_sel_hi:[1,0]
	v_pk_mul_f32 v[46:47], v[46:47], v[12:13] op_sel_hi:[1,0]
	s_waitcnt lgkmcnt(8)
	v_mfma_f32_16x16x32_f16 v[50:53], v[190:193], v[242:245], v[50:53]
	v_pk_mul_f32 v[44:45], v[44:45], v[12:13] op_sel_hi:[1,0]
	v_pk_mul_f32 v[42:43], v[42:43], v[12:13] op_sel_hi:[1,0]
	s_waitcnt lgkmcnt(7)
	v_mfma_f32_16x16x32_f16 v[46:49], v[194:197], v[242:245], v[46:49]
	v_pk_mul_f32 v[40:41], v[40:41], v[12:13] op_sel_hi:[1,0]
	s_waitcnt lgkmcnt(6)
	v_mfma_f32_16x16x32_f16 v[42:45], v[198:201], v[242:245], v[42:45]
	v_mov_b32_e32 v14, v114
	v_mov_b32_e32 v15, v115
	v_pk_mul_f32 v[38:39], v[38:39], v[12:13] op_sel_hi:[1,0]
	v_pk_mul_f32 v[36:37], v[36:37], v[12:13] op_sel_hi:[1,0]
	v_pk_mul_f32 v[34:35], v[34:35], v[12:13] op_sel_hi:[1,0]
	v_mfma_f32_16x16x32_f16 v[38:41], v[14:17], v[242:245], v[38:41]
	v_pk_mul_f32 v[32:33], v[32:33], v[12:13] op_sel_hi:[1,0]
	v_pk_mul_f32 v[30:31], v[30:31], v[12:13] op_sel_hi:[1,0]
	s_waitcnt lgkmcnt(5)
	v_mfma_f32_16x16x32_f16 v[34:37], v[230:233], v[242:245], v[34:37]
	v_pk_mul_f32 v[28:29], v[28:29], v[12:13] op_sel_hi:[1,0]
	s_waitcnt lgkmcnt(4)
	v_mfma_f32_16x16x32_f16 v[30:33], v[234:237], v[242:245], v[30:33]
	v_pk_mul_f32 v[26:27], v[26:27], v[12:13] op_sel_hi:[1,0]
	v_cvt_pk_f16_f32 v116, v22, v23
	v_cvt_pk_f16_f32 v117, v24, v25
	s_waitcnt lgkmcnt(3)
; template <int MIX>
; __device__ __forceinline__ void ch_scan(f32x4 (&St)[ChCfg<MIX>::K / 16], LAS unsigned char* B, int vg, int lane) {
;     typedef ChCfg<MIX> C; typedef RecCfg<MIX> RC; constexpr int K = C::K;
;     const int r = lane & 15, h = lane >> 4;
;     const LAS float* Gt = (const LAS float*)(B + C::B_G);
;     LAS float* Of = (LAS float*)B + RC::OFF_O;
; #pragma unroll
;     for (int mc = 0; mc < 4; ++mc) {
;         const int t0 = mc * 16;
;         f32x4 X = (f32x4){0.f, 0.f, 0.f, 0.f};
; #pragma unroll
;         for (int kb = 0; kb < K / 32; ++kb) {
;             const f16x8 a = *(const LAS f16x8*)(B + C::B_KH + (t0 + r) * C::RS + (kb * 32 + 8 * h) * 2);
;             const f16x8 b = *(const LAS f16x8*)(B + C::B_QH + (t0 + r) * C::RS + (kb * 32 + 8 * h) * 2);
;             X = __builtin_amdgcn_mfma_f32_16x16x32_f16(a, b, X, 0, 0, 0); }
;         const float gi = Gt[t0 + r]; const f32x4 gj = *(const LAS f32x4*)(Gt + t0 + 4 * h);
;         f16x8 pa, vb;
; #pragma unroll
;         for (int e = 0; e < 4; ++e) { const float d = fminf(gi - gj[e], 0.f); const float pv = (4 * h + e <= r) ? X[e] * __expf(d) : 0.f; pa[e] = (f16_t)pv; pa[4 + e] = (f16_t)0.f; }
;         { const u32x2 vv = *(const LAS u32x2*)(B + C::B_VT + (16 * vg + r) * C::TS_ + (t0 + 4 * h) * 2);
;           const u32x4 v4 = (u32x4){vv.x, vv.y, 0u, 0u}; vb = __builtin_bit_cast(f16x8, v4); }
;         f32x4 O = __builtin_amdgcn_mfma_f32_16x16x32_f16(pa, vb, (f32x4){0.f, 0.f, 0.f, 0.f}, 0, 0, 0);
; #pragma unroll
;         for (int m = 0; m < K / 32; ++m) {
;             const u32x2 qa0 = *(const LAS u32x2*)(B + C::B_QT + (t0 + r) * C::RS + (32 * m + 4 * h) * 2), qa1 = *(const LAS u32x2*)(B + C::B_QT + (t0 + r) * C::RS + (32 * m + 16 + 4 * h) * 2);
;             const u32x4 qa4 = (u32x4){qa0.x, qa0.y, qa1.x, qa1.y};
;             const u32x4 sb4 = (u32x4){pkh(St[2 * m][0], St[2 * m][1]), pkh(St[2 * m][2], St[2 * m][3]), pkh(St[2 * m + 1][0], St[2 * m + 1][1]), pkh(St[2 * m + 1][2], St[2 * m + 1][3])};
;             O = __builtin_amdgcn_mfma_f32_16x16x32_f16(__builtin_bit_cast(f16x8, qa4), __builtin_bit_cast(f16x8, sb4), O, 0, 0, 0); }
; #pragma unroll
;         for (int e = 0; e < 4; ++e) Of[(t0 + 4 * h + e) * 32 + 16 * vg + r] = O[e];
;         const float ge = __expf(Gt[t0 + 15]);
; #pragma unroll
;         for (int kt = 0; kt < K / 16; ++kt) {
	v_mfma_f32_16x16x32_f16 v[26:29], v[238:241], v[242:245], v[26:29]
	v_add_u32_e32 v59, v86, v76
	ds_read_b128 v[12:15], v101 offset:17408
	ds_read_b128 v[54:57], v101
	ds_read_b128 v[146:149], v101 offset:17472
	ds_read_b128 v[150:153], v101 offset:64
	ds_read_b128 v[154:157], v101 offset:17536
	ds_read_b128 v[158:161], v101 offset:128
	ds_read_b128 v[162:165], v101 offset:17600
	ds_read_b128 v[166:169], v101 offset:192
	ds_read_b32 v16, v83
	ds_read_b128 v[170:173], v84
	v_cvt_pk_f16_f32 v118, v50, v51
	v_cvt_pk_f16_f32 v119, v52, v53
	s_waitcnt lgkmcnt(8)
	v_mfma_f32_16x16x32_f16 v[12:15], v[12:15], v[54:57], 0
	v_add_u32_e32 v247, 0x8800, v102
	ds_read2_b64 v[174:177], v247 offset1:4
	ds_read2_b64 v[178:181], v247 offset0:8 offset1:12
	ds_read2_b64 v[182:185], v247 offset0:16 offset1:20
	ds_read2_b64 v[186:189], v247 offset0:24 offset1:28
	v_add_u32_e32 v248, v72, v85
	ds_read_b64 v[242:243], v248
	s_waitcnt lgkmcnt(11)
	v_mfma_f32_16x16x32_f16 v[12:15], v[146:149], v[150:153], v[12:15]
	s_waitcnt lgkmcnt(9)
	v_mfma_f32_16x16x32_f16 v[12:15], v[154:157], v[158:161], v[12:15]
	s_waitcnt lgkmcnt(7)
	v_mfma_f32_16x16x32_f16 v[12:15], v[162:165], v[166:169], v[12:15]
	s_waitcnt lgkmcnt(5)
	v_sub_f32_e32 v54, v16, v170
	v_min_f32_e32 v54, 0, v54
	v_mul_f32_e32 v54, 0x3fb8aa3b, v54
	v_exp_f32_e32 v54, v54
	s_nop 0
	s_nop 1
	v_fma_mixlo_f16 v12, v12, v54, 0
	v_sub_f32_e32 v54, v16, v171
	v_min_f32_e32 v54, 0, v54
	v_mul_f32_e32 v54, 0x3fb8aa3b, v54
	v_exp_f32_e32 v54, v54
	v_cndmask_b32_e64 v12, v12, 0, s[42:43]
	v_fma_mixlo_f16 v13, v13, v54, 0
	v_sub_f32_e32 v54, v16, v172
	v_sub_f32_e32 v16, v16, v173
	v_min_f32_e32 v54, 0, v54
	v_min_f32_e32 v16, 0, v16
	v_mul_f32_e32 v54, 0x3fb8aa3b, v54
	v_mul_f32_e32 v16, 0x3fb8aa3b, v16
	v_exp_f32_e32 v54, v54
	v_exp_f32_e32 v16, v16
	v_cndmask_b32_e64 v13, 0, v13, s[44:45]
	v_mov_b32_e32 v56, v17
	v_fma_mixlo_f16 v14, v14, v54, 0
	v_fma_mixlo_f16 v15, v15, v16, 0
	v_cndmask_b32_e64 v14, v14, 0, s[46:47]
	v_cndmask_b32_e64 v15, v15, 0, s[48:49]
	v_pack_b32_f16 v15, v14, v15
	v_pack_b32_f16 v14, v12, v13
	v_mov_b32_e32 v246, s13
	ds_read_b32 v246, v246
	v_add_u32_e32 v249, v86, v68
	ds_read2st64_b64 v[112:115], v249 offset0:102 offset1:120
	ds_read_b64 v[190:191], v59 offset:52224
	ds_read_b64 v[194:195], v59 offset:54528
	v_add_u32_e32 v250, v86, v77
	ds_read_b64 v[198:199], v250 offset:52224
	ds_read_b64 v[230:231], v249 offset:63744
	ds_read_b64 v[234:235], v105 offset:13824
	v_add_u32_e32 v251, v86, v78
	ds_read_b64 v[238:239], v251 offset:52224
	v_mov_b32_e32 v16, v17
	v_mov_b32_e32 v57, v17
	s_nop 0
	s_waitcnt lgkmcnt(8)
	v_mfma_f32_16x16x32_f16 v[12:15], v[14:17], v[242:245], 0
	s_nop 0
	v_mfma_f32_16x16x32_f16 v[12:15], v[174:177], v[116:119], v[12:15]
	v_cvt_pk_f16_f32 v116, v46, v47
	v_cvt_pk_f16_f32 v117, v48, v49
	v_cvt_pk_f16_f32 v118, v42, v43
	v_cvt_pk_f16_f32 v119, v44, v45
	s_nop 0
	s_nop 0
	v_mfma_f32_16x16x32_f16 v[12:15], v[178:181], v[116:119], v[12:15]
	v_cvt_pk_f16_f32 v116, v38, v39
	v_cvt_pk_f16_f32 v117, v40, v41
	v_cvt_pk_f16_f32 v118, v34, v35
	v_cvt_pk_f16_f32 v119, v36, v37
	s_nop 0
	s_nop 0
	v_mfma_f32_16x16x32_f16 v[12:15], v[182:185], v[116:119], v[12:15]
	v_cvt_pk_f16_f32 v116, v30, v31
	v_cvt_pk_f16_f32 v117, v32, v33
	v_cvt_pk_f16_f32 v118, v26, v27
	v_cvt_pk_f16_f32 v119, v28, v29
	v_mov_b32_e32 v16, v17
	s_nop 0
	v_mfma_f32_16x16x32_f16 v[12:15], v[186:189], v[116:119], v[12:15]
	s_nop 7
	ds_write_b32 v103, v12
	v_add_u32_e32 v12, 0x1000, v93
	ds_write2_b32 v12, v13, v14 offset0:32 offset1:64
	ds_write_b32 v104, v15
	s_waitcnt lgkmcnt(10)
	v_mul_f32_e32 v12, 0x3fb8aa3b, v246
	v_exp_f32_e32 v12, v12
	s_waitcnt lgkmcnt(9)
	v_mov_b32_e32 v14, v112
	v_mov_b32_e32 v15, v113
	v_pk_mul_f32 v[24:25], v[24:25], v[12:13] op_sel_hi:[1,0]
	v_pk_mul_f32 v[22:23], v[22:23], v[12:13] op_sel_hi:[1,0]
	v_pk_mul_f32 v[52:53], v[52:53], v[12:13] op_sel_hi:[1,0]
	v_pk_mul_f32 v[50:51], v[50:51], v[12:13] op_sel_hi:[1,0]
	v_mfma_f32_16x16x32_f16 v[22:25], v[14:17], v[242:245], v[22:25]
	v_pk_mul_f32 v[48:49], v[48:49], v[12:13] op_sel_hi:[1,0]
	v_pk_mul_f32 v[46:47], v[46:47], v[12:13] op_sel_hi:[1,0]
	s_waitcnt lgkmcnt(8)
	v_mfma_f32_16x16x32_f16 v[50:53], v[190:193], v[242:245], v[50:53]
	v_pk_mul_f32 v[44:45], v[44:45], v[12:13] op_sel_hi:[1,0]
	v_pk_mul_f32 v[42:43], v[42:43], v[12:13] op_sel_hi:[1,0]
	s_waitcnt lgkmcnt(7)
	v_mfma_f32_16x16x32_f16 v[46:49], v[194:197], v[242:245], v[46:49]
	v_pk_mul_f32 v[40:41], v[40:41], v[12:13] op_sel_hi:[1,0]
	s_waitcnt lgkmcnt(6)
	v_mfma_f32_16x16x32_f16 v[42:45], v[198:201], v[242:245], v[42:45]
	v_mov_b32_e32 v14, v114
	v_mov_b32_e32 v15, v115
	v_pk_mul_f32 v[38:39], v[38:39], v[12:13] op_sel_hi:[1,0]
	v_pk_mul_f32 v[36:37], v[36:37], v[12:13] op_sel_hi:[1,0]
	v_pk_mul_f32 v[34:35], v[34:35], v[12:13] op_sel_hi:[1,0]
	v_mfma_f32_16x16x32_f16 v[38:41], v[14:17], v[242:245], v[38:41]
	v_pk_mul_f32 v[32:33], v[32:33], v[12:13] op_sel_hi:[1,0]
	v_pk_mul_f32 v[30:31], v[30:31], v[12:13] op_sel_hi:[1,0]
	s_waitcnt lgkmcnt(5)
	v_mfma_f32_16x16x32_f16 v[34:37], v[230:233], v[242:245], v[34:37]
	v_pk_mul_f32 v[28:29], v[28:29], v[12:13] op_sel_hi:[1,0]
	s_waitcnt lgkmcnt(4)
	v_mfma_f32_16x16x32_f16 v[30:33], v[234:237], v[242:245], v[30:33]
	v_pk_mul_f32 v[26:27], v[26:27], v[12:13] op_sel_hi:[1,0]
	v_cvt_pk_f16_f32 v116, v22, v23
	v_cvt_pk_f16_f32 v117, v24, v25
	s_waitcnt lgkmcnt(3)
; template <int MIX>
; __device__ __forceinline__ void ch_scan(f32x4 (&St)[ChCfg<MIX>::K / 16], LAS unsigned char* B, int vg, int lane) {
;     typedef ChCfg<MIX> C; typedef RecCfg<MIX> RC; constexpr int K = C::K;
;     const int r = lane & 15, h = lane >> 4;
;     const LAS float* Gt = (const LAS float*)(B + C::B_G);
;     LAS float* Of = (LAS float*)B + RC::OFF_O;
; #pragma unroll
;     for (int mc = 0; mc < 4; ++mc) {
;         const int t0 = mc * 16;
;         f32x4 X = (f32x4){0.f, 0.f, 0.f, 0.f};
; #pragma unroll
;         for (int kb = 0; kb < K / 32; ++kb) {
;             const f16x8 a = *(const LAS f16x8*)(B + C::B_KH + (t0 + r) * C::RS + (kb * 32 + 8 * h) * 2);
;             const f16x8 b = *(const LAS f16x8*)(B + C::B_QH + (t0 + r) * C::RS + (kb * 32 + 8 * h) * 2);
;             X = __builtin_amdgcn_mfma_f32_16x16x32_f16(a, b, X, 0, 0, 0); }
;         const float gi = Gt[t0 + r]; const f32x4 gj = *(const LAS f32x4*)(Gt + t0 + 4 * h);
;         f16x8 pa, vb;
; #pragma unroll
;         for (int e = 0; e < 4; ++e) { const float d = fminf(gi - gj[e], 0.f); const float pv = (4 * h + e <= r) ? X[e] * __expf(d) : 0.f; pa[e] = (f16_t)pv; pa[4 + e] = (f16_t)0.f; }
;         { const u32x2 vv = *(const LAS u32x2*)(B + C::B_VT + (16 * vg + r) * C::TS_ + (t0 + 4 * h) * 2);
;           const u32x4 v4 = (u32x4){vv.x, vv.y, 0u, 0u}; vb = __builtin_bit_cast(f16x8, v4); }
;         f32x4 O = __builtin_amdgcn_mfma_f32_16x16x32_f16(pa, vb, (f32x4){0.f, 0.f, 0.f, 0.f}, 0, 0, 0);
; #pragma unroll
;         for (int m = 0; m < K / 32; ++m) {
;             const u32x2 qa0 = *(const LAS u32x2*)(B + C::B_QT + (t0 + r) * C::RS + (32 * m + 4 * h) * 2), qa1 = *(const LAS u32x2*)(B + C::B_QT + (t0 + r) * C::RS + (32 * m + 16 + 4 * h) * 2);
;             const u32x4 qa4 = (u32x4){qa0.x, qa0.y, qa1.x, qa1.y};
;             const u32x4 sb4 = (u32x4){pkh(St[2 * m][0], St[2 * m][1]), pkh(St[2 * m][2], St[2 * m][3]), pkh(St[2 * m + 1][0], St[2 * m + 1][1]), pkh(St[2 * m + 1][2], St[2 * m + 1][3])};
;             O = __builtin_amdgcn_mfma_f32_16x16x32_f16(__builtin_bit_cast(f16x8, qa4), __builtin_bit_cast(f16x8, sb4), O, 0, 0, 0); }
; #pragma unroll
;         for (int e = 0; e < 4; ++e) Of[(t0 + 4 * h + e) * 32 + 16 * vg + r] = O[e];
;         const float ge = __expf(Gt[t0 + 15]);
; #pragma unroll
;         for (int kt = 0; kt < K / 16; ++kt) {
	v_mfma_f32_16x16x32_f16 v[26:29], v[238:241], v[242:245], v[26:29]
	v_add_u32_e32 v59, v90, v76
	ds_read_b128 v[12:15], v106 offset:17408
	ds_read_b128 v[54:57], v106
	ds_read_b128 v[146:149], v106 offset:17472
	ds_read_b128 v[150:153], v106 offset:64
	ds_read_b128 v[154:157], v106 offset:17536
	ds_read_b128 v[158:161], v106 offset:128
	ds_read_b128 v[162:165], v106 offset:17600
	ds_read_b128 v[166:169], v106 offset:192
	ds_read_b32 v16, v87
	ds_read_b128 v[170:173], v88
	v_cvt_pk_f16_f32 v118, v50, v51
	v_cvt_pk_f16_f32 v119, v52, v53
	s_waitcnt lgkmcnt(8)
	v_mfma_f32_16x16x32_f16 v[12:15], v[12:15], v[54:57], 0
	v_add_u32_e32 v247, 0x8800, v107
	ds_read2_b64 v[174:177], v247 offset1:4
	ds_read2_b64 v[178:181], v247 offset0:8 offset1:12
	ds_read2_b64 v[182:185], v247 offset0:16 offset1:20
	ds_read2_b64 v[186:189], v247 offset0:24 offset1:28
	v_add_u32_e32 v248, v72, v89
	ds_read_b64 v[242:243], v248
	s_waitcnt lgkmcnt(11)
	v_mfma_f32_16x16x32_f16 v[12:15], v[146:149], v[150:153], v[12:15]
	s_waitcnt lgkmcnt(9)
	v_mfma_f32_16x16x32_f16 v[12:15], v[154:157], v[158:161], v[12:15]
	s_waitcnt lgkmcnt(7)
	v_mfma_f32_16x16x32_f16 v[12:15], v[162:165], v[166:169], v[12:15]
	s_waitcnt lgkmcnt(5)
	v_sub_f32_e32 v54, v16, v170
	v_min_f32_e32 v54, 0, v54
	v_mul_f32_e32 v54, 0x3fb8aa3b, v54
	v_exp_f32_e32 v54, v54
	s_nop 0
	s_nop 1
	v_fma_mixlo_f16 v12, v12, v54, 0
	v_sub_f32_e32 v54, v16, v171
	v_min_f32_e32 v54, 0, v54
	v_mul_f32_e32 v54, 0x3fb8aa3b, v54
	v_exp_f32_e32 v54, v54
	v_cndmask_b32_e64 v12, v12, 0, s[42:43]
	v_fma_mixlo_f16 v13, v13, v54, 0
	v_sub_f32_e32 v54, v16, v172
	v_sub_f32_e32 v16, v16, v173
	v_min_f32_e32 v54, 0, v54
	v_min_f32_e32 v16, 0, v16
	v_mul_f32_e32 v54, 0x3fb8aa3b, v54
	v_mul_f32_e32 v16, 0x3fb8aa3b, v16
	v_exp_f32_e32 v54, v54
	v_exp_f32_e32 v16, v16
	v_cndmask_b32_e64 v13, 0, v13, s[44:45]
	v_mov_b32_e32 v56, v17
	v_fma_mixlo_f16 v14, v14, v54, 0
	v_fma_mixlo_f16 v15, v15, v16, 0
	v_cndmask_b32_e64 v14, v14, 0, s[46:47]
	v_cndmask_b32_e64 v15, v15, 0, s[48:49]
	v_pack_b32_f16 v15, v14, v15
	v_pack_b32_f16 v14, v12, v13
	v_mov_b32_e32 v246, s17
	ds_read_b32 v246, v246
	v_add_u32_e32 v249, v90, v68
	ds_read2st64_b64 v[112:115], v249 offset0:102 offset1:120
	ds_read_b64 v[190:191], v59 offset:52224
	ds_read_b64 v[194:195], v59 offset:54528
	v_add_u32_e32 v250, v90, v77
	ds_read_b64 v[198:199], v250 offset:52224
	ds_read_b64 v[230:231], v249 offset:63744
	ds_read_b64 v[234:235], v110 offset:13824
	v_add_u32_e32 v251, v90, v78
	ds_read_b64 v[238:239], v251 offset:52224
	v_mov_b32_e32 v16, v17
	v_mov_b32_e32 v57, v17
	s_nop 0
	s_waitcnt lgkmcnt(8)
	v_mfma_f32_16x16x32_f16 v[12:15], v[14:17], v[242:245], 0
	s_nop 0
	v_mfma_f32_16x16x32_f16 v[12:15], v[174:177], v[116:119], v[12:15]
	v_cvt_pk_f16_f32 v116, v46, v47
	v_cvt_pk_f16_f32 v117, v48, v49
	v_cvt_pk_f16_f32 v118, v42, v43
	v_cvt_pk_f16_f32 v119, v44, v45
	s_nop 0
	s_nop 0
	v_mfma_f32_16x16x32_f16 v[12:15], v[178:181], v[116:119], v[12:15]
	v_cvt_pk_f16_f32 v116, v38, v39
	v_cvt_pk_f16_f32 v117, v40, v41
	v_cvt_pk_f16_f32 v118, v34, v35
	v_cvt_pk_f16_f32 v119, v36, v37
	s_nop 0
	s_nop 0
	v_mfma_f32_16x16x32_f16 v[12:15], v[182:185], v[116:119], v[12:15]
	v_cvt_pk_f16_f32 v116, v30, v31
	v_cvt_pk_f16_f32 v117, v32, v33
	v_cvt_pk_f16_f32 v118, v26, v27
	v_cvt_pk_f16_f32 v119, v28, v29
	v_mov_b32_e32 v16, v17
	s_nop 0
	v_mfma_f32_16x16x32_f16 v[12:15], v[186:189], v[116:119], v[12:15]
	s_nop 7
	ds_write_b32 v108, v12
	v_add_u32_e32 v12, 0x1800, v93
	ds_write2_b32 v12, v13, v14 offset0:32 offset1:64
	ds_write_b32 v109, v15
	s_waitcnt lgkmcnt(10)
	v_mul_f32_e32 v12, 0x3fb8aa3b, v246
	v_exp_f32_e32 v12, v12
	s_waitcnt lgkmcnt(9)
	v_mov_b32_e32 v14, v112
	v_mov_b32_e32 v15, v113
	v_pk_mul_f32 v[24:25], v[24:25], v[12:13] op_sel_hi:[1,0]
	v_pk_mul_f32 v[22:23], v[22:23], v[12:13] op_sel_hi:[1,0]
	v_pk_mul_f32 v[52:53], v[52:53], v[12:13] op_sel_hi:[1,0]
	v_pk_mul_f32 v[50:51], v[50:51], v[12:13] op_sel_hi:[1,0]
	v_mfma_f32_16x16x32_f16 v[22:25], v[14:17], v[242:245], v[22:25]
	v_pk_mul_f32 v[48:49], v[48:49], v[12:13] op_sel_hi:[1,0]
	v_pk_mul_f32 v[46:47], v[46:47], v[12:13] op_sel_hi:[1,0]
	s_waitcnt lgkmcnt(8)
	v_mfma_f32_16x16x32_f16 v[50:53], v[190:193], v[242:245], v[50:53]
	v_pk_mul_f32 v[44:45], v[44:45], v[12:13] op_sel_hi:[1,0]
	v_pk_mul_f32 v[42:43], v[42:43], v[12:13] op_sel_hi:[1,0]
	s_waitcnt lgkmcnt(7)
	v_mfma_f32_16x16x32_f16 v[46:49], v[194:197], v[242:245], v[46:49]
	v_pk_mul_f32 v[40:41], v[40:41], v[12:13] op_sel_hi:[1,0]
	s_waitcnt lgkmcnt(6)
	v_mfma_f32_16x16x32_f16 v[42:45], v[198:201], v[242:245], v[42:45]
	v_mov_b32_e32 v14, v114
	v_mov_b32_e32 v15, v115
	v_pk_mul_f32 v[38:39], v[38:39], v[12:13] op_sel_hi:[1,0]
	v_pk_mul_f32 v[36:37], v[36:37], v[12:13] op_sel_hi:[1,0]
	v_pk_mul_f32 v[34:35], v[34:35], v[12:13] op_sel_hi:[1,0]
	v_mfma_f32_16x16x32_f16 v[38:41], v[14:17], v[242:245], v[38:41]
	v_pk_mul_f32 v[32:33], v[32:33], v[12:13] op_sel_hi:[1,0]
	v_pk_mul_f32 v[30:31], v[30:31], v[12:13] op_sel_hi:[1,0]
	s_waitcnt lgkmcnt(5)
	v_mfma_f32_16x16x32_f16 v[34:37], v[230:233], v[242:245], v[34:37]
	v_pk_mul_f32 v[28:29], v[28:29], v[12:13] op_sel_hi:[1,0]
	s_waitcnt lgkmcnt(4)
	v_mfma_f32_16x16x32_f16 v[30:33], v[234:237], v[242:245], v[30:33]
	v_pk_mul_f32 v[26:27], v[26:27], v[12:13] op_sel_hi:[1,0]
	s_nop 0
	s_waitcnt lgkmcnt(3)
	v_mfma_f32_16x16x32_f16 v[26:29], v[238:241], v[242:245], v[26:29]
	s_waitcnt lgkmcnt(0)
	s_branch .LBB0_178

; __device__ __forceinline__ float hload(const f16_t* p) { return (float)(*p); }
; template <int MIX, bool SAMPLE>
; __device__ __forceinline__ void rec_load(Raw<MIX>& R, const f16_t* proj, int chunk, int sg, int head, int vcol0) {
;     ...
;     } else if constexpr (MIX == 1) {
;         R.q = *(const u32x4*)(rowp + C_GQKV + head * 64 + cgi * 8);
;         R.k = *(const u32x4*)(rowp + C_GQKV + 256 + head * 64 + cgi * 8);
;         R.v = *(const u32x2*)(rowp + C_GQKV + 512 + head * 64 + vcol0 + cgi * 4);
;         R.ga = hload(rowp + C_GA + head); R.gb = hload(rowp + C_GB + head);
;     ...
;     if constexpr (MIX == 1) {
;         constexpr int BUF = C::OFF_O + 2048;
;         rec_load<MIX, false>(R, proj, 0, sg, head, vcol0);
;         rec_process<MIX, false>(R, par, l, L, 0, sg, head);
;         __syncthreads();
;         rec_load<MIX, false>(R, proj, 1, sg, head, vcol0);
.LBB0_410:
	s_or_b64 exec, exec, s[4:5]
	v_mov_b32_e32 v0, v202
	s_waitcnt lgkmcnt(0)
	s_barrier
	s_lshl_b32 s2, s30, 6
	v_ashrrev_i32_e32 v1, 3, v0
	v_and_b32_e32 v2, 7, v0
	v_add3_u32 v3, v1, s10, 64
	v_mov_b64_e32 v[0:1], s[54:55]
	s_lshl_b32 s11, s34, 5
	v_mad_i64_i32 v[12:13], s[4:5], v3, s18, v[0:1]
	s_lshl_b32 s78, s2, 1
	s_mov_b32 s57, s79
	v_lshl_add_u64 v[8:9], v[12:13], 0, s[78:79]
	v_lshlrev_b32_e32 v0, 4, v2
	v_mov_b32_e32 v1, v17
	s_lshl_b32 s4, s11, 1
	s_mov_b32 s5, s79
	v_lshl_add_u64 v[12:13], v[12:13], 0, s[56:57]
	v_lshlrev_b32_e32 v16, 3, v2
	s_waitcnt vmcnt(0)
	v_lshl_add_u64 v[4:5], v[8:9], 0, v[0:1]
	v_lshl_add_u64 v[8:9], v[8:9], 0, s[4:5]
	v_add_co_u32_e32 v12, vcc, s20, v12
	v_lshl_add_u64 v[8:9], v[8:9], 0, v[16:17]
	s_nop 0
	v_addc_co_u32_e32 v13, vcc, 0, v13, vcc
	global_load_dwordx4 v[0:3], v[4:5], off offset:2048
	s_nop 0
	global_load_dwordx4 v[4:7], v[4:5], off offset:2560
	v_bfe_u32 v21, v10, 4, 2
	global_load_dwordx2 v[8:9], v[8:9], off offset:3072
	v_ashrrev_i32_e32 v11, 4, v10
	global_load_ushort v14, v[12:13], off
	v_and_b32_e32 v20, 15, v10
	global_load_ushort v12, v[12:13], off offset:8
	v_and_b32_e32 v13, 2, v10
	v_and_b32_e32 v22, -4, v11
	s_add_i32 s2, 0, 0x8000
	v_cmp_gt_i32_e64 s[42:43], 32, v22
	s_mov_b32 s12, 0
	v_cmp_gt_u32_e64 s[44:45], 8, v20
	v_cmp_eq_u32_e64 s[48:49], 0, v13
	s_or_b32 s13, s10, 0x80
	v_lshl_add_u32 v26, v20, 4, 0
	s_waitcnt vmcnt(1)
	v_mov_b32_e32 v23, v14
	s_waitcnt vmcnt(0)
	v_mov_b32_e32 v24, v12
	v_and_b32_e32 v12, 4, v10
	v_and_b32_e32 v10, 1, v10
	v_cmp_eq_u32_e64 s[50:51], 0, v10
	v_lshlrev_b32_e32 v10, 2, v11
	v_lshlrev_b32_e32 v11, 2, v21
	v_and_or_b32 v10, v10, -16, v11
	v_add_u32_e32 v25, s2, v10
	v_lshlrev_b32_e32 v11, 7, v20
	s_add_i32 s2, 0, 0xc400
	v_add3_u32 v27, v10, v11, s2
	v_mov_b32_e32 v10, 0
	v_cmp_eq_u32_e64 s[46:47], 0, v12
	v_mov_b32_e32 v11, v10
	v_mov_b32_e32 v12, v10
	v_mov_b32_e32 v13, v10
	s_bitcmp1_b32 s12, 0
	s_cselect_b32 s22, 0x3900, 0
	s_and_saveexec_b64 s[6:7], s[42:43]
	s_cbranch_execz .LBB0_413

; #define LAS __attribute__((address_space(3)))
; __device__ __forceinline__ float sigmoidf_(float x) { return 1.0f / (1.0f + __expf(-x)); }
; __device__ __forceinline__ float softplusf_(float x) { return x > 20.f ? x : log1pf(expf(x)); }
; __device__ __forceinline__ float red8(float x) { x = red4(x); x += dppf<0x141>(x); return x; }
; __device__ __forceinline__ void u4f(const u32x4& u, float (&f)[8]) { h2f(u.x, f[0], f[1]); h2f(u.y, f[2], f[3]); h2f(u.z, f[4], f[5]); h2f(u.w, f[6], f[7]); }
; __device__ __forceinline__ void u2f(const u32x2& u, float (&f)[4]) { h2f(u.x, f[0], f[1]); h2f(u.y, f[2], f[3]); }
; template <int MIX, bool SAMPLE>
; __device__ __forceinline__ void rec_process(const Raw<MIX>& R, const MixPar& par, int l, LAS float* L, int chunk, int sg, int head) {
;     ...
;     } else if constexpr (MIX == 1) {
;         float q[8], k[8], v[4]; u4f(R.q, q); u4f(R.k, k); u2f(R.v, v);
;         float sq = 0.f, sk = 0.f;
; #pragma unroll
;         for (int i = 0; i < 8; ++i) { sq += q[i] * q[i]; sk += k[i] * k[i]; }
;         sq = red8(sq); sk = red8(sk);
;         const float rq = rsqrtf(sq + EPS) * 0.125f, rk = rsqrtf(sk + EPS);
;         float kq = 0.f;
; #pragma unroll
;         for (int i = 0; i < 8; ++i) { q[i] *= rq; k[i] *= rk; kq += q[i] * k[i]; }
;         kq = red8(kq);
;         *(LAS f32x4*)(L + C::OFF_Q + s * 64 + cgi * 8) = (f32x4){q[0], q[1], q[2], q[3]}; *(LAS f32x4*)(L + C::OFF_Q + s * 64 + cgi * 8 + 4) = (f32x4){q[4], q[5], q[6], q[7]};
;         *(LAS f32x4*)(L + C::OFF_K + s * 64 + cgi * 8) = (f32x4){k[0], k[1], k[2], k[3]}; *(LAS f32x4*)(L + C::OFF_K + s * 64 + cgi * 8 + 4) = (f32x4){k[4], k[5], k[6], k[7]};
;         *(LAS f32x4*)(L + C::OFF_V + s * 32 + cgi * 4) = (f32x4){v[0], v[1], v[2], v[3]};
;         if (cgi == 0) { const float a = expf(-par.f[0] * softplusf_(R.ga + par.f[1]));
;             *(LAS f32x4*)(L + C::OFF_SC + s * 4) = (f32x4){a, sigmoidf_(R.gb), kq, 0.f}; }
.LBB0_413:
	s_or_b64 exec, exec, s[6:7]
	s_add_i32 s2, s12, 1
	s_cmp_lg_u32 s12, 31
	s_cbranch_scc0 .LBB0_420
	s_waitcnt vmcnt(2)
	v_cvt_f32_f16_e32 v23, v23
	v_cvt_f32_f16_e32 v24, v24
	v_cvt_f32_f16_sdwa v31, v0 dst_sel:DWORD dst_unused:UNUSED_PAD src0_sel:WORD_1
	v_cvt_f32_f16_e32 v30, v0
	s_waitcnt vmcnt(1)
	v_cvt_f32_f16_sdwa v47, v4 dst_sel:DWORD dst_unused:UNUSED_PAD src0_sel:WORD_1
	v_cvt_f32_f16_e32 v46, v4
	v_cvt_f32_f16_sdwa v41, v1 dst_sel:DWORD dst_unused:UNUSED_PAD src0_sel:WORD_1
	v_cvt_f32_f16_e32 v40, v1
	v_cvt_f32_f16_sdwa v49, v5 dst_sel:DWORD dst_unused:UNUSED_PAD src0_sel:WORD_1
	v_cvt_f32_f16_e32 v48, v5
	v_cvt_f32_f16_sdwa v15, v2 dst_sel:DWORD dst_unused:UNUSED_PAD src0_sel:WORD_1
	v_cvt_f32_f16_e32 v14, v2
	v_cvt_f32_f16_sdwa v43, v6 dst_sel:DWORD dst_unused:UNUSED_PAD src0_sel:WORD_1
	v_cvt_f32_f16_e32 v42, v6
	v_pk_mul_f32 v[38:39], v[30:31], v[30:31]
	v_pk_mul_f32 v[54:55], v[46:47], v[46:47]
	v_cvt_f32_f16_sdwa v37, v3 dst_sel:DWORD dst_unused:UNUSED_PAD src0_sel:WORD_1
	v_cvt_f32_f16_e32 v36, v3
	v_cvt_f32_f16_sdwa v45, v7 dst_sel:DWORD dst_unused:UNUSED_PAD src0_sel:WORD_1
	v_cvt_f32_f16_e32 v44, v7
	v_pk_mul_f32 v[50:51], v[40:41], v[40:41]
	v_pk_mul_f32 v[56:57], v[48:49], v[48:49]
	v_mov_b32_e32 v58, v54
	v_mov_b32_e32 v59, v38
	v_mov_b32_e32 v38, v55
	v_pk_add_f32 v[38:39], v[58:59], v[38:39]
	v_mov_b32_e32 v54, v56
	v_mov_b32_e32 v55, v50
	v_pk_mul_f32 v[28:29], v[14:15], v[14:15]
	v_pk_mul_f32 v[32:33], v[42:43], v[42:43]
	v_pk_add_f32 v[38:39], v[54:55], v[38:39]
	v_mov_b32_e32 v50, v57
	v_pk_add_f32 v[38:39], v[50:51], v[38:39]
	v_mov_b32_e32 v50, v32
	v_mov_b32_e32 v51, v28
	v_pk_mul_f32 v[34:35], v[36:37], v[36:37]
	v_pk_mul_f32 v[52:53], v[44:45], v[44:45]
	v_pk_add_f32 v[38:39], v[50:51], v[38:39]
	v_mov_b32_e32 v28, v33
	v_pk_add_f32 v[28:29], v[28:29], v[38:39]
	v_mov_b32_e32 v32, v52
	v_mov_b32_e32 v33, v34
	v_pk_add_f32 v[28:29], v[32:33], v[28:29]
	v_mov_b32_e32 v34, v53
	v_pk_add_f32 v[28:29], v[34:35], v[28:29]
	s_bitcmp1_b32 s2, 0
	s_cselect_b32 s3, 0xe400, 0
	v_mov_b32_dpp v33, v29 quad_perm:[1,0,3,2] row_mask:0xf bank_mask:0xf bound_ctrl:1
	v_mov_b32_dpp v32, v28 quad_perm:[1,0,3,2] row_mask:0xf bank_mask:0xf bound_ctrl:1
	v_pk_add_f32 v[28:29], v[28:29], v[32:33]
	s_add_i32 s3, s3, 0
	s_nop 0
	v_mov_b32_dpp v33, v29 quad_perm:[2,3,0,1] row_mask:0xf bank_mask:0xf bound_ctrl:1
	v_mov_b32_dpp v32, v28 quad_perm:[2,3,0,1] row_mask:0xf bank_mask:0xf bound_ctrl:1
	v_pk_add_f32 v[28:29], v[28:29], v[32:33]
	s_nop 1
	v_mov_b32_dpp v33, v29 row_half_mirror row_mask:0xf bank_mask:0xf bound_ctrl:1
	v_mov_b32_dpp v32, v28 row_half_mirror row_mask:0xf bank_mask:0xf bound_ctrl:1
	v_pk_add_f32 v[28:29], v[28:29], v[32:33]
	s_nop 0
	v_pk_add_f32 v[32:33], v[28:29], s[66:67] op_sel_hi:[1,0]
	v_mov_b32_e32 v29, v202
	v_mul_f32_e32 v16, 0x4b800000, v33
	v_cmp_gt_f32_e32 vcc, s16, v33
	s_nop 0
	v_ashrrev_i32_e32 v28, 3, v29
	v_cndmask_b32_e32 v16, v33, v16, vcc
	v_rsq_f32_e32 v16, v16
	s_nop 0
	v_mul_f32_e32 v33, 0x45800000, v16
	v_cndmask_b32_e32 v16, v16, v33, vcc
	v_mul_f32_e32 v33, 0x4b800000, v32
	v_cmp_gt_f32_e32 vcc, s16, v32
	v_mul_f32_e32 v16, 0x3e000000, v16
	v_pk_mul_f32 v[34:35], v[16:17], v[14:15] op_sel_hi:[0,1]
	v_cndmask_b32_e32 v32, v32, v33, vcc
	v_rsq_f32_e32 v38, v32
	v_pk_mul_f32 v[30:31], v[16:17], v[30:31] op_sel_hi:[0,1]
	v_pk_mul_f32 v[32:33], v[16:17], v[40:41] op_sel_hi:[0,1]
	v_pk_mul_f32 v[36:37], v[16:17], v[36:37] op_sel_hi:[0,1]
	v_mul_f32_e32 v14, 0x45800000, v38
	v_cndmask_b32_e32 v14, v38, v14, vcc
	v_pk_mul_f32 v[38:39], v[14:15], v[46:47] op_sel_hi:[0,1]
	v_pk_mul_f32 v[40:41], v[30:31], v[38:39]
	s_nop 0
	v_add_f32_e32 v15, 0, v40
	v_add_f32_e32 v15, v41, v15
	v_pk_mul_f32 v[40:41], v[14:15], v[48:49] op_sel_hi:[0,1]
	v_pk_mul_f32 v[46:47], v[32:33], v[40:41]
	v_cvt_f32_f16_sdwa v49, v9 dst_sel:DWORD dst_unused:UNUSED_PAD src0_sel:WORD_1
	v_add_f32_e32 v15, v46, v15
	v_add_f32_e32 v15, v47, v15
	v_pk_mul_f32 v[42:43], v[14:15], v[42:43] op_sel_hi:[0,1]
	v_pk_mul_f32 v[46:47], v[34:35], v[42:43]
	v_cvt_f32_f16_e32 v48, v9
	v_add_f32_e32 v15, v46, v15
	v_pk_mul_f32 v[44:45], v[14:15], v[44:45] op_sel_hi:[0,1]
	v_add_f32_e32 v16, v47, v15
	v_pk_mul_f32 v[14:15], v[36:37], v[44:45]
	v_cvt_f32_f16_sdwa v47, v8 dst_sel:DWORD dst_unused:UNUSED_PAD src0_sel:WORD_1
	v_add_f32_e32 v14, v14, v16
	v_and_b32_e32 v16, 7, v29
	v_add_f32_e32 v14, v15, v14
	v_cvt_f32_f16_e32 v46, v8
	v_lshlrev_b32_e32 v29, 8, v28
	v_lshlrev_b32_e32 v50, 5, v16
	v_add_f32_dpp v14, v14, v14 quad_perm:[1,0,3,2] row_mask:0xf bank_mask:0xf bound_ctrl:1
	v_add3_u32 v29, s3, v29, v50
	ds_write_b128 v29, v[30:33]
	ds_write_b128 v29, v[34:37] offset:16
	ds_write_b128 v29, v[38:41] offset:16384
	ds_write_b128 v29, v[42:45] offset:16400
	v_add_f32_dpp v14, v14, v14 quad_perm:[2,3,0,1] row_mask:0xf bank_mask:0xf bound_ctrl:1
	v_lshlrev_b32_e32 v29, 7, v28
	v_lshlrev_b32_e32 v30, 4, v16
	v_mov_b32_dpp v15, v14 row_half_mirror row_mask:0xf bank_mask:0xf bound_ctrl:1
	v_add3_u32 v29, s3, v29, v30
	v_cmp_eq_u32_e32 vcc, 0, v16
	ds_write_b128 v29, v[46:49] offset:32768
	s_and_saveexec_b64 s[6:7], vcc
	s_cbranch_execz .LBB0_418
; __device__ __forceinline__ float softplusf_(float x) { return x > 20.f ? x : log1pf(expf(x)); }
; template <int MIX, bool SAMPLE>
; __device__ __forceinline__ void rec_process(const Raw<MIX>& R, const MixPar& par, int l, LAS float* L, int chunk, int sg, int head) {
;     ...
;         if (cgi == 0) { const float a = expf(-par.f[0] * softplusf_(R.ga + par.f[1]));
	v_add_f32_e32 v16, v18, v23
	v_cmp_nlt_f32_e32 vcc, s23, v16
	s_and_saveexec_b64 s[8:9], vcc
	s_cbranch_execz .LBB0_417
	v_mul_f32_e32 v29, 0x3fb8aa3b, v16
	v_rndne_f32_e32 v30, v29
	v_sub_f32_e32 v31, v29, v30
	v_fma_f32 v29, v16, s19, -v29
	v_fmac_f32_e32 v29, 0x32a5705f, v16
	v_add_f32_e32 v29, v31, v29
	v_cvt_i32_f32_e32 v30, v30
	v_exp_f32_e32 v29, v29
	v_cmp_ngt_f32_e32 vcc, s96, v16
	v_ldexp_f32 v29, v29, v30
	s_nop 0
	v_cndmask_b32_e32 v29, 0, v29, vcc
	v_cmp_nlt_f32_e32 vcc, s97, v16
	s_nop 1
	v_cndmask_b32_e32 v16, v216, v29, vcc
	v_add_f32_e32 v29, 1.0, v16
	v_add_f32_e32 v30, -1.0, v29
	v_sub_f32_e32 v31, v30, v29
	v_add_f32_e32 v31, 1.0, v31
	v_sub_f32_e32 v30, v16, v30
	v_add_f32_e32 v32, v30, v31
	v_frexp_mant_f32_e32 v33, v29
	v_cvt_f64_f32_e32 v[30:31], v29
	v_frexp_exp_i32_f64_e32 v30, v[30:31]
	v_cmp_gt_f32_e32 vcc, s62, v33
	s_nop 1
	v_subbrev_co_u32_e32 v38, vcc, 0, v30, vcc
	v_sub_u32_e32 v30, 0, v38
	v_ldexp_f32 v29, v29, v30
	v_ldexp_f32 v30, v32, v30
	v_add_f32_e32 v32, -1.0, v29
	v_add_f32_e32 v31, 1.0, v32
	v_sub_f32_e32 v31, v29, v31
	v_add_f32_e32 v33, v30, v31
	v_add_f32_e32 v31, 1.0, v29
	v_add_f32_e32 v34, -1.0, v31
	v_sub_f32_e32 v29, v29, v34
	v_add_f32_e32 v29, v30, v29
	v_add_f32_e32 v39, v31, v29
	v_rcp_f32_e32 v40, v39
	v_sub_f32_e32 v30, v31, v39
	v_add_f32_e32 v31, v32, v33
	v_add_f32_e32 v29, v29, v30
	v_mul_f32_e32 v42, v31, v40
	v_sub_f32_e32 v30, v32, v31
	v_mul_f32_e32 v32, v39, v42
	v_fma_f32 v34, v42, v39, -v32
	v_fmac_f32_e32 v34, v42, v29
	v_add_f32_e32 v41, v33, v30
	v_add_f32_e32 v30, v32, v34
	v_sub_f32_e32 v33, v31, v30
	v_pk_add_f32 v[36:37], v[30:31], v[32:33] neg_lo:[0,1] neg_hi:[0,1]
	v_mov_b32_e32 v35, v30
	v_pk_add_f32 v[30:31], v[36:37], v[34:35] neg_lo:[0,1] neg_hi:[0,1]
	v_cmp_neq_f32_e32 vcc, s21, v16
	v_add_f32_e32 v31, v41, v31
	v_add_f32_e32 v30, v30, v31
	v_add_f32_e32 v31, v33, v30
	v_mul_f32_e32 v41, v40, v31
	v_mul_f32_e32 v32, v39, v41
	v_fma_f32 v34, v41, v39, -v32
	v_fmac_f32_e32 v34, v41, v29
	v_sub_f32_e32 v29, v33, v31
	v_add_f32_e32 v29, v30, v29
	v_add_f32_e32 v30, v32, v34
	v_sub_f32_e32 v33, v31, v30
	v_pk_add_f32 v[36:37], v[30:31], v[32:33] neg_lo:[0,1] neg_hi:[0,1]
	v_mov_b32_e32 v35, v30
	v_pk_add_f32 v[30:31], v[36:37], v[34:35] neg_lo:[0,1] neg_hi:[0,1]
	s_nop 0
	v_add_f32_e32 v29, v29, v31
	v_add_f32_e32 v29, v30, v29
	v_add_f32_e32 v31, v42, v41
	v_add_f32_e32 v29, v33, v29
	v_sub_f32_e32 v30, v31, v42
	v_mul_f32_e32 v29, v40, v29
	v_sub_f32_e32 v30, v41, v30
	v_add_f32_e32 v29, v30, v29
	v_add_f32_e32 v32, v31, v29
	v_mul_f32_e32 v34, v32, v32
	v_fmamk_f32 v30, v34, 0x3e9b6dac, v204
	v_fmaak_f32 v139, v34, v30, 0x3f2aaada
	v_cvt_f32_i32_e32 v30, v38
	v_sub_f32_e32 v31, v32, v31
	v_sub_f32_e32 v29, v29, v31
	v_mul_f32_e32 v31, v32, v34
	v_pk_mul_f32 v[34:35], v[30:31], v[138:139]
	v_ldexp_f32 v33, v32, 1
	v_fma_f32 v32, v30, s63, -v34
	v_fmac_f32_e32 v32, 0xb102e308, v30
	v_pk_add_f32 v[30:31], v[34:35], v[32:33]
	v_ldexp_f32 v29, v29, 1
	v_sub_f32_e32 v33, v31, v33
	v_sub_f32_e32 v33, v35, v33
	v_add_f32_e32 v37, v29, v33
	v_mov_b32_e32 v36, v34
	v_pk_add_f32 v[34:35], v[30:31], v[34:35] neg_lo:[0,1] neg_hi:[0,1]
	v_pk_add_f32 v[38:39], v[30:31], v[36:37]
	v_mov_b32_e32 v33, v30
	v_mov_b32_e32 v35, v39
	v_pk_add_f32 v[40:41], v[32:33], v[34:35] neg_lo:[0,1] neg_hi:[0,1]
	v_pk_add_f32 v[32:33], v[32:33], v[34:35]
	v_mov_b32_e32 v36, v37
	v_pk_add_f32 v[34:35], v[32:33], v[30:31] op_sel:[1,0] op_sel_hi:[0,1] neg_lo:[0,1] neg_hi:[0,1]
	v_pk_add_f32 v[42:43], v[38:39], v[34:35] op_sel_hi:[1,0] neg_lo:[0,1] neg_hi:[0,1]
	v_mov_b32_e32 v38, v39
	v_mov_b32_e32 v39, v33
	v_pk_mov_b32 v[34:35], v[30:31], v[34:35] op_sel:[1,0]
	v_mov_b32_e32 v37, v30
	v_pk_add_f32 v[34:35], v[38:39], v[34:35] neg_lo:[0,1] neg_hi:[0,1]
	v_mov_b32_e32 v42, v40
	v_pk_add_f32 v[30:31], v[36:37], v[34:35] neg_lo:[0,1] neg_hi:[0,1]
	v_mov_b32_e32 v41, v33
	v_pk_add_f32 v[34:35], v[42:43], v[30:31]
	s_nop 0
	v_pk_add_f32 v[36:37], v[34:35], v[34:35] op_sel:[0,1] op_sel_hi:[1,0]
	s_nop 0
	v_pk_add_f32 v[32:33], v[32:33], v[36:37] op_sel:[1,0] op_sel_hi:[0,1]
	v_mov_b32_e32 v35, v32
	v_pk_add_f32 v[38:39], v[34:35], v[40:41] neg_lo:[0,1] neg_hi:[0,1]
	v_mov_b32_e32 v31, v36
	v_sub_f32_e32 v29, v34, v38
	v_pk_add_f32 v[30:31], v[30:31], v[38:39] neg_lo:[0,1] neg_hi:[0,1]
	v_sub_f32_e32 v29, v40, v29
	v_add_f32_e32 v29, v30, v29
	v_add_f32_e32 v29, v29, v31
	v_add_f32_e32 v29, v32, v29
	v_cndmask_b32_e32 v29, v216, v29, vcc
	v_cmp_lt_f32_e64 vcc, |v16|, s64
	s_nop 1
	v_cndmask_b32_e32 v16, v29, v16, vcc

; __device__ __forceinline__ float hload(const f16_t* p) { return (float)(*p); }
; template <int MIX, bool SAMPLE>
; __device__ __forceinline__ void rec_load(Raw<MIX>& R, const f16_t* proj, int chunk, int sg, int head, int vcol0) {
;     ...
;     } else if constexpr (MIX == 1) {
;         R.q = *(const u32x4*)(rowp + C_GQKV + head * 64 + cgi * 8);
;         R.k = *(const u32x4*)(rowp + C_GQKV + 256 + head * 64 + cgi * 8);
;         R.v = *(const u32x2*)(rowp + C_GQKV + 512 + head * 64 + vcol0 + cgi * 4);
;         R.ga = hload(rowp + C_GA + head); R.gb = hload(rowp + C_GB + head);
;     ...
;             if (c + 1 < SEQ / 64) { rec_process<MIX, false>(R, par, l, L + ((c + 1) & 1) * BUF, c + 1, sg, head);
;                 if (c + 2 < SEQ / 64) rec_load<MIX, false>(R, proj, c + 2, sg, head, vcol0);
;                 else if (DO_SAMPLE) rec_load<MIX, true>(R, proj, 0, sg, head, vcol0); }
.LBB0_418:
	s_or_b64 exec, exec, s[6:7]
	s_cmp_gt_u32 s12, 29
	s_cbranch_scc1 .LBB0_420
	v_mov_b32_e32 v0, v202
	s_lshl_b32 s3, s12, 6
	s_add_i32 s3, s13, s3
	v_ashrrev_i32_e32 v1, 3, v0
	v_and_b32_e32 v4, 7, v0
	v_add_u32_e32 v2, s3, v1
	v_mov_b64_e32 v[0:1], s[54:55]
	v_mad_i64_i32 v[0:1], s[6:7], v2, s18, v[0:1]
	v_lshl_add_u64 v[2:3], v[0:1], 0, s[78:79]
	s_mov_b32 s5, s79
	s_mov_b32 s57, s79
	v_lshlrev_b32_e32 v16, 3, v4
	v_lshl_add_u64 v[6:7], v[2:3], 0, s[4:5]
	v_lshl_add_u64 v[0:1], v[0:1], 0, s[56:57]
	v_lshl_add_u64 v[6:7], v[6:7], 0, v[16:17]
	v_add_co_u32_e32 v0, vcc, 0x1000, v0
	v_lshlrev_b32_e32 v4, 4, v4
	s_nop 0
	v_addc_co_u32_e32 v1, vcc, 0, v1, vcc
	global_load_dwordx2 v[8:9], v[6:7], off offset:3072
	global_load_ushort v23, v[0:1], off
	global_load_ushort v24, v[0:1], off offset:8
	v_mov_b32_e32 v5, v17
	v_lshl_add_u64 v[4:5], v[2:3], 0, v[4:5]
	global_load_dwordx4 v[0:3], v[4:5], off offset:2048
	s_nop 0
	global_load_dwordx4 v[4:7], v[4:5], off offset:2560
